# SSD phase: chunk C tile also lands by direct global->LDS loads (3-deep ring; third buffer split in two 8 KB halves by l-tile pair), no more 128-bit LDS fill writes for B/C
# baseline (speedup 1.0000x reference)
; #define LAS __attribute__((address_space(3)))
; __device__ __forceinline__ int launder_v(int v) { asm volatile("" : "+v"(v)); return v; }
; __device__ __forceinline__ int grid_x() { int g = (int)gridDim.x; asm volatile("" : "+s"(g)); return g; }
; __device__ __forceinline__ void phase_ssd(const Params& P, int seg, unsigned char* smem) {
;     ...
;     const int tid = launder_v(threadIdx.x), lane = tid & 63, w = tid >> 6, fr = lane & 15, fq = lane >> 4;
;     const unsigned lds0 = (unsigned)(size_t)(LAS unsigned char*)smem;
;     bf16* StS = (bf16*)(smem + T_ST); float* acS = (float*)(smem + T_AC);
;     const int lt = w >> 1, pt = w & 1, tq = (lane & 15) >> 2, tp = lane & 3;
;     if (__builtin_amdgcn_readfirstlane(tid) >= 256) __builtin_amdgcn_s_setprio(1);
;     const int gx = grid_x();
.LBB0_292:
	v_readlane_b32 s14, v253, 47
	v_readlane_b32 s15, v253, 48
	s_mov_b32 s9, s82
	s_andn2_b64 vcc, exec, s[14:15]
	v_cndmask_b32_e64 v4, 0, 1, s[14:15]
	v_cmp_ne_u32_e64 s[16:17], 1, v4
	s_nop 1
	v_writelane_b32 v255, s16, 7
	s_nop 1
	v_writelane_b32 v255, s17, 8
	s_cbranch_vccnz .LBB0_338
	s_mov_b64 exec, -1
	s_mov_b64 s[0:1], s[80:81]
	s_mov_b32 s63, s82
	v_readlane_b32 s24, v254, 38
	v_readlane_b32 s52, v252, 28
	v_readlane_b32 s53, v252, 29
	v_and_b32_e32 v140, 63, v172
	v_lshrrev_b32_e32 v141, 6, v172
	v_and_b32_e32 v142, 15, v172
	v_bfe_u32 v143, v172, 4, 2
	v_bfe_u32 v144, v172, 2, 2
	v_and_b32_e32 v145, 3, v172
	v_lshrrev_b32_e32 v146, 7, v172
	v_lshrrev_b32_e32 v147, 8, v172
	v_xor_b32_e32 v146, v146, v147
	v_bfe_u32 v147, v172, 6, 1
	v_readfirstlane_b32 s73, v141
	s_nop 3
	s_lshr_b32 s55, s73, 1
	s_lshr_b32 s65, s73, 2
	s_xor_b32 s55, s55, s65
	s_lshl_b32 s81, s73, 10
	v_lshrrev_b32_e32 v138, 4, v172
	v_and_b32_e32 v139, 7, v138
	v_lshlrev_b32_e32 v139, 1, v139
	v_xor_b32_e32 v139, v139, v142
	v_lshlrev_b32_e32 v139, 4, v139
	v_lshl_add_u32 v169, v138, 8, v139
	v_lshrrev_b32_e32 v139, 3, v172
	v_and_b32_e32 v148, 7, v172
	v_mul_u32_u24_e32 v171, 80, v139
	v_lshl_add_u32 v171, v148, 3, v171
	v_mul_u32_u24_e32 v184, 72, v139
	v_lshl_add_u32 v184, v148, 3, v184
	v_lshlrev_b32_e32 v186, 2, v139
	v_add_u32_e32 v186, 0x1d800, v186
	v_and_b32_e32 v149, 7, v142
	v_lshlrev_b32_e32 v149, 1, v149
	v_lshl_add_u32 v160, v147, 4, v142
	v_lshlrev_b32_e32 v160, 8, v160
	v_add_u32_e32 v160, 0x19800, v160
	v_add_u32_e32 v138, 0, v143
	v_xor_b32_e32 v138, v138, v149
	v_lshlrev_b32_e32 v138, 4, v138
	v_lshl_add_u32 v187, v142, 8, v138
	v_add_u32_e32 v195, v160, v138
	v_add_u32_e32 v138, 4, v143
	v_xor_b32_e32 v138, v138, v149
	v_lshlrev_b32_e32 v138, 4, v138
	v_lshl_add_u32 v188, v142, 8, v138
	v_add_u32_e32 v196, v160, v138
	v_add_u32_e32 v138, 8, v143
	v_xor_b32_e32 v138, v138, v149
	v_lshlrev_b32_e32 v138, 4, v138
	v_lshl_add_u32 v189, v142, 8, v138
	v_add_u32_e32 v197, v160, v138
	v_add_u32_e32 v138, 12, v143
	v_xor_b32_e32 v138, v138, v149
	v_lshlrev_b32_e32 v138, 4, v138
	v_lshl_add_u32 v190, v142, 8, v138
	v_add_u32_e32 v198, v160, v138
	v_lshlrev_b32_e32 v199, 2, v142
	v_add_u32_e32 v199, 0x1d800, v199
	v_lshlrev_b32_e32 v200, 4, v143
	v_add_u32_e32 v200, 0x1d800, v200
	v_lshl_add_u32 v138, v143, 2, v144
	v_mul_u32_u24_e32 v201, 80, v138
	v_lshl_add_u32 v201, v147, 5, v201
	v_lshl_add_u32 v201, v145, 3, v201
	v_mul_u32_u24_e32 v203, 72, v142
	v_lshl_add_u32 v203, v147, 5, v203
	v_lshl_add_u32 v203, v143, 3, v203
	v_mul_u32_u24_e32 v205, 80, v138
	v_lshl_add_u32 v205, v145, 3, v205
	v_and_b32_e32 v139, 7, v138
	v_lshlrev_b32_e32 v139, 1, v139
	v_lshrrev_b32_e32 v148, 1, v145
	v_and_b32_e32 v160, 1, v145
	v_lshlrev_b32_e32 v160, 3, v160
	v_lshl_add_u32 v160, v138, 8, v160
	v_and_b32_e32 v151, 3, v141
	v_lshl_add_u32 v149, v151, 2, v148
	v_xor_b32_e32 v149, v149, v139
	v_lshl_add_u32 v207, v149, 4, v160
	v_lshl_add_u32 v149, v151, 2, v148
	v_add_u32_e32 v149, 2, v149
	v_xor_b32_e32 v149, v149, v139
	v_lshl_add_u32 v208, v149, 4, v160
	v_and_b32_e32 v139, 7, v142
	v_lshlrev_b32_e32 v139, 1, v139
	v_lshrrev_b32_e32 v148, 1, v143
	v_and_b32_e32 v160, 1, v143
	v_lshlrev_b32_e32 v160, 3, v160
	v_lshl_add_u32 v160, v142, 8, v160
	v_add_u32_e32 v160, 0x19800, v160
	v_lshl_add_u32 v149, v151, 2, v148
	v_xor_b32_e32 v149, v149, v139
	v_lshl_add_u32 v211, v149, 4, v160
	v_lshl_add_u32 v149, v151, 2, v148
	v_add_u32_e32 v149, 2, v149
	v_xor_b32_e32 v149, v149, v139
	v_lshl_add_u32 v212, v149, 4, v160
	v_add_u32_e32 v170, 0xcc00, v169
	v_add_u32_e32 v174, 0xcc00, v171
	v_add_u32_e32 v185, 0xcc00, v184
	v_add_u32_e32 v202, 0xcc00, v201
	v_add_u32_e32 v204, 0xcc00, v203
	v_add_u32_e32 v206, 0xcc00, v205
	v_add_u32_e32 v191, 0xcc00, v187
	v_add_u32_e32 v192, 0xcc00, v188
	v_add_u32_e32 v193, 0xcc00, v189
	v_add_u32_e32 v194, 0xcc00, v190
	v_add_u32_e32 v209, 0xcc00, v207
	v_add_u32_e32 v210, 0xcc00, v208
	v_lshlrev_b32_e32 v138, 2, v143
	v_add_u32_e32 v139, 0, v138
	v_cmp_le_u32_e64 s[14:15], v139, v142
	v_add_u32_e32 v139, 1, v138
	v_cmp_le_u32_e64 s[16:17], v139, v142
	v_add_u32_e32 v139, 2, v138
	v_cmp_le_u32_e64 s[22:23], v139, v142
	v_add_u32_e32 v139, 3, v138
	v_cmp_le_u32_e64 s[34:35], v139, v142
	v_lshlrev_b32_e32 v168, 9, v142
	v_lshl_add_u32 v168, v151, 7, v168
	v_lshl_add_u32 v168, v143, 4, v168
	s_cmp_eq_u32 s24, 0
	s_cselect_b32 s60, 1, 0
	s_add_u32 s39, s60, 64
	s_mov_b32 s18, s2
; #define GAS __attribute__((address_space(1)))
; __device__ __forceinline__ void phase_ssd(const Params& P, int seg, unsigned char* smem) {
;     ...
;     for (int item = blockIdx.x; item < 256; item += gx) {
;         const int xcd = item & 7, ix = item >> 3, bg = xcd * 2 + (ix >> 4), b = bg >> 3, g = bg & 7, h = g * 8 + ((ix & 15) >> 1), ph = ix & 1;
;         const float Dh = P.d_skip[h];
;         const GAS float* stg = state + (size_t)(seg & 1) * (2 * 64 * 64 * 128) + ((size_t)(b * 64 + h) * 64 + ph * 32) * 128;
;         GAS float* stw = state + (size_t)((seg + 1) & 1) * (2 * 64 * 64 * 128) + ((size_t)(b * 64 + h) * 64 + ph * 32) * 128;
;         f32x4 st[2];
; #pragma unroll
;         for (int p2 = 0; p2 < 2; ++p2)
; #pragma unroll
;             for (int j = 0; j < 4; ++j) st[p2][j] = (seg == 0) ? 0.f : stg[(size_t)(p2 * 16 + fq * 4 + j) * 128 + w * 16 + fr];
;         __syncthreads();
; #pragma unroll
;         for (int p2 = 0; p2 < 2; ++p2)
; #pragma unroll
;             for (int j = 0; j < 4; ++j) StS[(p2 * 16 + fq * 4 + j) * 136 + w * 16 + fr] = (bf16)f2bf(st[p2][j]);
;         const int nchunks = TSEG / 64 + (seg == 0 ? 1 : 0);
;         struct Pre { v4u Br[2], Cr[2]; v2u Xr, Zr; float dtl, acl, alast, aclane; }; Pre RA, RB;
;         auto chunk_row0 = [&](int ci) -> int { return (seg == 0) ? (ci == 0 ? RS : b * TSEG + (ci - 1) * 64) : b * TSEG + ci * 64; };
;         auto load_chunk = [&](int ci, Pre& R) { const int row0 = chunk_row0(ci);
; #pragma unroll
;             for (int i = 0; i < 2; ++i) { const int q = tid + 512 * i, l = q >> 4, c8 = q & 15; const GAS bf16* rp = xconv + (size_t)(row0 + l) * DXBC + g * 128 + c8 * 8;
;                 R.Br[i] = *(const GAS v4u*)(rp + 4096); R.Cr[i] = *(const GAS v4u*)(rp + 5120); }
;             { const int l = tid >> 3, p4 = (tid & 7) * 4; R.Xr = *(const GAS v2u*)(xconv + (size_t)(row0 + l) * DXBC + h * 64 + ph * 32 + p4);
;               R.Zr = __builtin_nontemporal_load((const GAS v2u*)(proj + (size_t)(row0 + l) * NPROJ + OFF_Z + h * 64 + ph * 32 + p4));
;               R.dtl = dtv[(size_t)(row0 + l) * 64 + h]; R.acl = acv[(size_t)(row0 + l) * 64 + h]; }
;             R.alast = acv[(size_t)(row0 + 63) * 64 + h]; R.aclane = acv[(size_t)(row0 + lane) * 64 + h]; };
;         load_chunk(0, RA); if (nchunks > 1) load_chunk(1, RB);
.Lssd_item:
	v_and_b32_e32 v142, 15, v172
	v_bfe_u32 v143, v172, 4, 2
	v_lshrrev_b32_e32 v146, 7, v172
	v_lshrrev_b32_e32 v147, 8, v172
	v_xor_b32_e32 v146, v146, v147
	v_bfe_u32 v147, v172, 6, 1
	v_lshrrev_b32_e32 v138, 4, v172
	v_lshrrev_b32_e32 v139, 3, v172
	v_and_b32_e32 v148, 7, v172
	v_mul_u32_u24_e32 v162, 0x3000, v138
	v_lshl_add_u32 v162, v142, 4, v162
	v_add_u32_e32 v162, 0x2000, v162
	v_mul_u32_u24_e32 v140, 0x3000, v139
	v_lshl_add_u32 v140, v148, 3, v140
	v_mul_u32_u24_e32 v144, 0xa000, v139
	v_lshl_add_u32 v144, v148, 3, v144
	v_add_u32_e32 v144, 0x3000, v144
	v_lshlrev_b32_e32 v145, 8, v139
	v_and_b32_e32 v149, 63, v172
	v_lshlrev_b32_e32 v149, 8, v149
	v_lshl_add_u32 v160, v146, 4, v142
	v_lshlrev_b32_e32 v160, 13, v160
	v_lshl_add_u32 v160, v147, 5, v160
	v_lshl_add_u32 v160, v143, 3, v160
	s_and_b32 s65, s18, 7
	s_lshr_b32 s66, s18, 3
	s_lshr_b32 s67, s66, 4
	s_lshl_b32 s65, s65, 1
	s_add_u32 s65, s65, s67
	s_lshr_b32 s72, s65, 3
	s_and_b32 s70, s65, 7
	s_and_b32 s71, s66, 1
	s_bfe_u32 s67, s66, 0x30001
	s_lshl_b32 s69, s70, 3
	s_add_u32 s69, s69, s67
	s_lshl_b32 s20, s72, 12
	s_cmp_eq_u32 s60, 1
	s_cselect_b32 s57, 0x2000, s20
	s_lshl_b32 s65, s70, 8
	v_add_u32_e32 v161, s65, v162
	v_add_u32_e32 v162, 0x60000, v161
	v_and_b32_e32 v146, 7, v138
	v_lshlrev_b32_e32 v146, 1, v146
	v_xor_b32_e32 v146, v146, v142
	v_sub_u32_e32 v146, v146, v142
	v_lshl_add_u32 v219, v146, 4, v161
	v_add_u32_e32 v220, 0x60000, v219
	v_add_u32_e32 v225, 2048, v219
	v_add_u32_e32 v226, 2048, v220
	s_lshl_b32 s65, s69, 7
	s_lshl_b32 s66, s71, 6
	s_add_u32 s65, s65, s66
	v_add_u32_e32 v163, s65, v140
	v_add_u32_e32 v164, s65, v144
	v_add_u32_e32 v167, s65, v160
	s_lshl_b32 s66, s69, 2
	v_add_u32_e32 v165, s66, v145
	s_add_u32 s67, s66, 0x3f00
	v_mov_b32_e32 v166, s67
	s_load_dword s61, s[52:53], s66
	s_lshl_b32 s65, s72, 6
	s_add_u32 s65, s65, s69
	s_lshl_b32 s65, s65, 6
	s_lshl_b32 s66, s71, 5
	s_add_u32 s65, s65, s66
	s_lshl_b32 s65, s65, 9
	s_add_u32 s65, s65, 0x3aef9000
	s_and_b32 s66, s24, 1
	s_mul_i32 s67, s66, 0x400000
	s_xor_b32 s66, s66, 1
	s_mul_i32 s68, s66, 0x400000
	s_add_u32 s68, s68, s65
	s_add_u32 s50, s0, s68
	s_addc_u32 s51, s1, 0
	s_add_u32 s67, s67, s65
	s_add_u32 s48, s0, s67
	s_addc_u32 s49, s1, 0
	v_mov_b32_e32 v8, 0
	v_mov_b32_e32 v9, 0
	v_mov_b32_e32 v10, 0
	v_mov_b32_e32 v11, 0
	v_mov_b32_e32 v12, 0
	v_mov_b32_e32 v13, 0
	v_mov_b32_e32 v14, 0
	v_mov_b32_e32 v15, 0
	v_mov_b32_e32 v16, 0
	v_mov_b32_e32 v17, 0
	v_mov_b32_e32 v18, 0
	v_mov_b32_e32 v19, 0
	v_mov_b32_e32 v20, 0
	v_mov_b32_e32 v21, 0
	v_mov_b32_e32 v22, 0
	v_mov_b32_e32 v23, 0
	s_cmp_eq_u32 s60, 1
	s_cbranch_scc1 .Lssd_nostate
	s_cmp_ge_u32 s55, 2
	s_cbranch_scc1 .Lssd_nostate
	v_add_u32_e32 v141, 0x2000, v168
	global_load_dwordx4 v[8:11], v168, s[48:49]
	global_load_dwordx4 v[12:15], v141, s[48:49]
	global_load_dwordx4 v[16:19], v168, s[48:49] offset:64
	global_load_dwordx4 v[20:23], v141, s[48:49] offset:64
.Lssd_nostate:
	s_mov_b32 s54, 0
	s_mov_b32 s66, 0
	s_sub_u32 s65, s66, s60
	s_lshl_b32 s65, s65, 6
	s_add_u32 s65, s65, s20
	s_cmp_eq_u32 s66, 0
	s_cselect_b32 s56, s57, s65
	s_mul_i32 s65, s56, 0x3000
	s_add_u32 s65, s65, 0x29fe1000
	s_add_u32 s40, s0, s65
	s_addc_u32 s41, s1, 0
	s_mul_i32 s65, s56, 0xa000
	s_add_u32 s65, s65, 0x134e1000
	s_add_u32 s42, s0, s65
	s_addc_u32 s43, s1, 0
	s_mul_i32 s65, s56, 0x100
	s_add_u32 s65, s65, 0x302e1000
	s_add_u32 s44, s0, s65
	s_addc_u32 s45, s1, 0
	s_mul_i32 s65, s56, 0x100
	s_add_u32 s65, s65, 0x3b79e000
	s_add_u32 s46, s0, s65
	s_addc_u32 s47, s1, 0
	s_mov_b32 s77, 0x4000
	s_mov_b32 s78, 0x10c00
	s_mov_b32 s79, 0x21100
	s_mov_b32 s82, 0x0
	s_mov_b32 s83, 0xcc00
	s_mov_b32 s84, 0x25100
	s_mov_b32 s85, 0x2000
	s_mov_b32 s86, 0xec00
	s_mov_b32 s87, 0x1da00
	s_add_u32 m0, s82, s81
	s_nop 0
	global_load_lds_dwordx4 v225, s[40:41]
	s_add_u32 m0, s85, s81
	s_nop 0
	global_load_lds_dwordx4 v226, s[40:41]
	s_add_u32 m0, s77, s81
	s_nop 0
	global_load_lds_dwordx4 v219, s[40:41]
	s_add_u32 m0, m0, 0x2000
	s_nop 0
	global_load_lds_dwordx4 v220, s[40:41]
	global_load_dwordx2 v[4:5], v163, s[40:41]
	global_load_dwordx2 v[36:37], v164, s[42:43] nt
	global_load_dword v6, v165, s[44:45]
	global_load_dword v116, v165, s[46:47]
	global_load_dword v117, v166, s[46:47]
	s_mov_b32 s66, 1
	s_sub_u32 s65, s66, s60
	s_lshl_b32 s65, s65, 6
	s_add_u32 s65, s65, s20
	s_cmp_eq_u32 s66, 0
	s_cselect_b32 s67, s57, s65
	s_mul_i32 s65, s67, 0x3000
	s_add_u32 s65, s65, 0x29fe1000
	s_add_u32 s40, s0, s65
	s_addc_u32 s41, s1, 0
	s_mul_i32 s65, s67, 0xa000
	s_add_u32 s65, s65, 0x134e1000
	s_add_u32 s42, s0, s65
	s_addc_u32 s43, s1, 0
	s_mul_i32 s65, s67, 0x100
	s_add_u32 s65, s65, 0x302e1000
	s_add_u32 s44, s0, s65
	s_addc_u32 s45, s1, 0
	s_mul_i32 s65, s67, 0x100
	s_add_u32 s65, s65, 0x3b79e000
	s_add_u32 s46, s0, s65
	s_addc_u32 s47, s1, 0
	s_add_u32 m0, s83, s81
	s_nop 0
	global_load_lds_dwordx4 v225, s[40:41]
	s_add_u32 m0, s86, s81
	s_nop 0
	global_load_lds_dwordx4 v226, s[40:41]
	s_add_u32 m0, s78, s81
	s_nop 0
	global_load_lds_dwordx4 v219, s[40:41]
	s_add_u32 m0, m0, 0x2000
	s_nop 0
	global_load_lds_dwordx4 v220, s[40:41]
	global_load_dwordx2 v[132:133], v163, s[40:41]
	global_load_dwordx2 v[134:135], v164, s[42:43] nt
	global_load_dword v118, v165, s[44:45]
	global_load_dword v136, v165, s[46:47]
	global_load_dword v137, v166, s[46:47]
	s_mov_b32 s66, 2
	s_sub_u32 s65, s66, s60
	s_lshl_b32 s65, s65, 6
	s_add_u32 s65, s65, s20
	s_cmp_eq_u32 s66, 0
	s_cselect_b32 s67, s57, s65
	s_mul_i32 s65, s67, 0x3000
	s_add_u32 s65, s65, 0x29fe1000
	s_add_u32 s40, s0, s65
	s_addc_u32 s41, s1, 0
	s_mul_i32 s65, s67, 0xa000
	s_add_u32 s65, s65, 0x134e1000
	s_add_u32 s42, s0, s65
	s_addc_u32 s43, s1, 0
	s_mul_i32 s65, s67, 0x100
	s_add_u32 s65, s65, 0x302e1000
	s_add_u32 s44, s0, s65
	s_addc_u32 s45, s1, 0
	s_mul_i32 s65, s67, 0x100
	s_add_u32 s65, s65, 0x3b79e000
	s_add_u32 s46, s0, s65
	s_addc_u32 s47, s1, 0
	s_waitcnt vmcnt(0)
	s_waitcnt lgkmcnt(0)
	s_barrier
	s_cmp_ge_u32 s55, 2
	s_cbranch_scc1 .Lssd_noimg
	v_cvt_pk_bf16_f32 v140, v8, v9
	v_cvt_pk_bf16_f32 v141, v10, v11
	v_cvt_pk_bf16_f32 v142, v12, v13
	v_cvt_pk_bf16_f32 v143, v14, v15
	v_cvt_pk_bf16_f32 v144, v16, v17
	v_cvt_pk_bf16_f32 v145, v18, v19
	v_cvt_pk_bf16_f32 v146, v20, v21
	v_cvt_pk_bf16_f32 v147, v22, v23
	ds_write_b64 v211, v[140:141]
	ds_write_b64 v211, v[142:143] offset:4096
	ds_write_b64 v212, v[144:145]
	ds_write_b64 v212, v[146:147] offset:4096
	s_waitcnt lgkmcnt(0)
; __device__ __forceinline__ unsigned cvt_pk_bf16(float lo, float hi) { unsigned r; asm volatile("v_cvt_pk_bf16_f32 %0, %1, %2" : "=v"(r) : "v"(lo), "v"(hi)); return r; }
; __device__ __forceinline__ void phase_ssd(const Params& P, int seg, unsigned char* smem) {
;     ...
;             { const float e2 = __expf(R.alast - R.acl);
; #pragma unroll
;               for (int i = 0; i < 2; ++i) { const int q = tid + 512 * i, l = q >> 4, c8 = q & 15; *(v4u*)(sb + T_CS + l * 272 + c8 * 16) = R.Cr[i]; *(v4u*)(sb + T_BS + l * 272 + c8 * 16) = R.Br[i]; }
;               const int l = tid >> 3, p4 = (tid & 7) * 4;
;               const float x0 = bflo(R.Xr.x) * R.dtl, x1 = bfhi(R.Xr.x) * R.dtl, x2 = bflo(R.Xr.y) * R.dtl, x3 = bfhi(R.Xr.y) * R.dtl;
;               v2u d; d.x = cvt_pk_bf16(x0, x1); d.y = cvt_pk_bf16(x2, x3); *(v2u*)(sb + T_XD + l * 80 + p4 * 2) = d;
;               v2u e; e.x = cvt_pk_bf16(x0 * e2, x1 * e2); e.y = cvt_pk_bf16(x2 * e2, x3 * e2); *(v2u*)(sb + T_XE + l * 80 + p4 * 2) = e;
;               *(v2u*)(sb + T_XS + l * 64 + p4 * 2) = R.Xr; *(v2u*)(sb + T_ZS + l * 64 + p4 * 2) = R.Zr;
;               if (w == 0) acP[lane] = R.aclane; }
;             BAR_LDS();
;             if (ci + 2 < nchunks) load_chunk(ci + 2, R);
;             bf16x8 cf[4];
; #pragma unroll
;             for (int k = 0; k < 4; ++k) cf[k] = *(const bf16x8*)(sb + T_CS + (lt * 16 + fr) * 272 + (k * 32 + fq * 8) * 2);
;             f32x4 yo = {0.f, 0.f, 0.f, 0.f};
; #pragma unroll
;             for (int k = 0; k < 4; ++k) { const bf16x8 bb = *(const bf16x8*)((const unsigned char*)StR + (pt * 16 + fr) * 272 + (k * 32 + fq * 8) * 2); yo = mfma16(cf[k], bb, yo); }
; { const f32x4 a4 = *(const f32x4*)(acP + lt * 16 + fq * 4);
; #pragma unroll
;               for (int j = 0; j < 4; ++j) yo[j] *= __expf(a4[j]); }
;             const float acl_fr = acP[lt * 16 + fr]; const int lrow = lt * 16 + fr;
; #pragma unroll
;             for (int t = 0; t < 2; ++t) {
;                 if (2 * t <= lt) {
;                     v2u xb0, xb1;
;                     { const unsigned a0 = lds0 + par * T_BUF + T_XD + (32 * t + 4 * fq + tq) * 80 + (pt * 16 + 4 * tp) * 2, a1 = a0 + 16 * 80; TR_ISSUE(xb0, a0); TR_ISSUE(xb1, a1); }
;                     float m[8];
;                     { f32x4 s0 = {0.f, 0.f, 0.f, 0.f}, s1 = {0.f, 0.f, 0.f, 0.f};
; #pragma unroll
.Lssd_noimg:
	v_sub_f32_e32 v156, v117, v116
	v_mul_f32_e32 v156, 0x3fb8aa3b, v156
	v_exp_f32_e32 v156, v156
	v_lshlrev_b32_e32 v152, 16, v4
	v_and_b32_e32 v153, 0xffff0000, v4
	v_lshlrev_b32_e32 v154, 16, v5
	v_and_b32_e32 v155, 0xffff0000, v5
	v_mul_f32_e32 v152, v152, v6
	v_mul_f32_e32 v153, v153, v6
	v_mul_f32_e32 v154, v154, v6
	v_mul_f32_e32 v155, v155, v6
	v_cvt_pk_bf16_f32 v158, v152, v153
	v_cvt_pk_bf16_f32 v159, v154, v155
	ds_write_b64 v171, v[158:159] offset:32768
	v_mul_f32_e32 v152, v152, v156
	v_mul_f32_e32 v153, v153, v156
	v_mul_f32_e32 v154, v154, v156
	v_mul_f32_e32 v155, v155, v156
	v_cvt_pk_bf16_f32 v148, v152, v153
	v_cvt_pk_bf16_f32 v149, v154, v155
	ds_write_b64 v171, v[148:149] offset:37888
	ds_write_b64 v184, v[4:5] offset:43008
	ds_write_b64 v184, v[36:37] offset:47616
	v_mul_f32_e32 v157, 0x3fb8aa3b, v116
	ds_write_b32 v186, v157
	v_mul_f32_e32 v150, 0x3fb8aa3b, v117
	v_exp_f32_e32 v150, v150
	s_waitcnt lgkmcnt(0)
	s_barrier
	s_cmp_eq_u32 s55, 1
	s_cbranch_scc1 .Lssd_loop1
	s_cmp_eq_u32 s55, 2
	s_cbranch_scc1 .Lssd_loop2
	s_cmp_eq_u32 s55, 3
	s_cbranch_scc1 .Lssd_loop3
.Lssd_loop0:
	v_add_u32_e32 v213, s77, v187
	v_add_u32_e32 v214, s77, v188
	v_add_u32_e32 v215, s77, v189
	v_add_u32_e32 v216, s77, v190
	v_add_u32_e32 v217, s77, v207
	v_add_u32_e32 v218, s77, v208
	v_add_u32_e32 v221, s82, v187
	v_add_u32_e32 v222, s82, v188
	v_add_u32_e32 v223, s82, v189
	v_add_u32_e32 v224, s82, v190
	ds_read_b128 v[28:31], v221
	ds_read_b128 v[32:35], v222
	ds_read_b128 v[40:43], v223
	ds_read_b128 v[44:47], v224
	ds_read_b128 v[48:51], v195
	ds_read_b128 v[52:55], v196
	ds_read_b128 v[56:59], v197
	ds_read_b128 v[60:63], v198
	ds_read_b32 v151, v199
	ds_read_b64_tr_b16 v[96:97], v217
	ds_read_b64_tr_b16 v[98:99], v217 offset:4096
	ds_read_b64_tr_b16 v[100:101], v217 offset:8192
	ds_read_b64_tr_b16 v[102:103], v217 offset:12288
	ds_read_b64_tr_b16 v[104:105], v218
	ds_read_b64_tr_b16 v[106:107], v218 offset:4096
	s_waitcnt lgkmcnt(11)
	ds_read_b64_tr_b16 v[108:109], v218 offset:8192
	ds_read_b64_tr_b16 v[110:111], v218 offset:12288
	ds_read_b64_tr_b16 v[112:113], v205 offset:37888
	ds_read_b64_tr_b16 v[114:115], v205 offset:39168
	s_waitcnt lgkmcnt(11)
	ds_read_b64_tr_b16 v[124:125], v205 offset:37920
	ds_read_b64_tr_b16 v[126:127], v205 offset:39200
	ds_read_b64_tr_b16 v[120:121], v205 offset:40448
	ds_read_b64_tr_b16 v[122:123], v205 offset:41728
	s_add_u32 m0, s84, s81
	s_nop 0
	global_load_lds_dwordx4 v225, s[40:41]
	s_waitcnt lgkmcnt(11)
	ds_read_b64_tr_b16 v[128:129], v205 offset:40480
	ds_read_b64_tr_b16 v[130:131], v205 offset:41760
	ds_read_b128 v[64:67], v213
	ds_read_b128 v[68:71], v214
	s_waitcnt lgkmcnt(11)
	ds_read_b128 v[72:75], v215
	s_add_u32 m0, s87, s81
	s_nop 0
	global_load_lds_dwordx4 v226, s[40:41]
	ds_read_b128 v[76:79], v216
	v_mfma_f32_16x16x32_bf16 v[24:27], v[48:51], v[28:31], 0
	v_mfma_f32_16x16x32_bf16 v[24:27], v[52:55], v[32:35], v[24:27]
	v_mfma_f32_16x16x32_bf16 v[24:27], v[56:59], v[40:43], v[24:27]
	v_mfma_f32_16x16x32_bf16 v[24:27], v[60:63], v[44:47], v[24:27]
	ds_read_b64_tr_b16 v[56:57], v201 offset:32768
	s_add_u32 m0, s79, s81
	s_nop 0
	global_load_lds_dwordx4 v219, s[40:41]
	ds_read_b64_tr_b16 v[58:59], v201 offset:34048
	v_mul_f32_e32 v8, v8, v150
	v_mul_f32_e32 v9, v9, v150
	v_mul_f32_e32 v10, v10, v150
	v_mul_f32_e32 v11, v11, v150
	v_mul_f32_e32 v12, v12, v150
	s_add_u32 m0, m0, 0x2000
	s_nop 0
	global_load_lds_dwordx4 v220, s[40:41]
	v_mul_f32_e32 v13, v13, v150
	v_mul_f32_e32 v14, v14, v150
	v_mul_f32_e32 v15, v15, v150
	v_mul_f32_e32 v16, v16, v150
	v_mul_f32_e32 v17, v17, v150
	global_load_dwordx2 v[4:5], v163, s[40:41]
	v_mul_f32_e32 v18, v18, v150
	v_mul_f32_e32 v19, v19, v150
	v_mul_f32_e32 v20, v20, v150
	v_mul_f32_e32 v21, v21, v150
	v_mul_f32_e32 v22, v22, v150
	v_mul_f32_e32 v23, v23, v150
	global_load_dwordx2 v[36:37], v164, s[42:43] nt
	s_waitcnt lgkmcnt(12)
	v_mfma_f32_16x16x32_bf16 v[8:11], v[96:99], v[112:115], v[8:11]
	s_waitcnt lgkmcnt(10)
	v_mfma_f32_16x16x32_bf16 v[12:15], v[96:99], v[124:127], v[12:15]
	v_mfma_f32_16x16x32_bf16 v[16:19], v[104:107], v[112:115], v[16:19]
	v_mfma_f32_16x16x32_bf16 v[20:23], v[104:107], v[124:127], v[20:23]
	s_waitcnt lgkmcnt(8)
	v_mfma_f32_16x16x32_bf16 v[8:11], v[100:103], v[120:123], v[8:11]
	s_waitcnt lgkmcnt(6)
	v_mfma_f32_16x16x32_bf16 v[12:15], v[100:103], v[128:131], v[12:15]
	global_load_dword v6, v165, s[44:45]
	v_mfma_f32_16x16x32_bf16 v[16:19], v[108:111], v[120:123], v[16:19]
	v_mfma_f32_16x16x32_bf16 v[20:23], v[108:111], v[128:131], v[20:23]
	ds_read_b128 v[96:99], v200
	ds_read_b64 v[124:125], v203 offset:43008
	ds_read_b64 v[126:127], v203 offset:47616
	s_waitcnt lgkmcnt(8)
	v_mfma_f32_16x16x32_bf16 v[48:51], v[64:67], v[28:31], 0
	global_load_dword v116, v165, s[46:47]
	s_waitcnt lgkmcnt(7)
	v_mfma_f32_16x16x32_bf16 v[48:51], v[68:71], v[32:35], v[48:51]
	s_waitcnt lgkmcnt(6)
	v_mfma_f32_16x16x32_bf16 v[48:51], v[72:75], v[40:43], v[48:51]
	s_waitcnt lgkmcnt(5)
	v_mfma_f32_16x16x32_bf16 v[48:51], v[76:79], v[44:47], v[48:51]
	v_exp_f32_e32 v160, v151
	s_nop 0
	v_mul_f32_e32 v24, v24, v160
	global_load_dword v117, v166, s[46:47]
	v_mul_f32_e32 v25, v25, v160
	v_mul_f32_e32 v26, v26, v160
	v_mul_f32_e32 v27, v27, v160
	v_cvt_pk_bf16_f32 v140, v8, v9
	v_cvt_pk_bf16_f32 v141, v10, v11
	v_cvt_pk_bf16_f32 v142, v12, v13
	s_add_u32 s66, s54, 3
	s_cmp_lt_u32 s66, s39
	s_cselect_b32 s74, 0xc0000, 0
	s_cselect_b32 s75, 0x280000, 0
	s_cselect_b32 s76, 0x4000, 0
	s_add_u32 s40, s40, s74
	s_addc_u32 s41, s41, 0
	s_add_u32 s42, s42, s75
	s_addc_u32 s43, s43, 0
	s_add_u32 s44, s44, s76
	s_addc_u32 s45, s45, 0
	s_add_u32 s46, s46, s76
	s_addc_u32 s47, s47, 0
	v_cvt_pk_bf16_f32 v143, v14, v15
	v_cvt_pk_bf16_f32 v144, v16, v17
	s_waitcnt vmcnt(10)
; __device__ __forceinline__ bf16 f2bfh(float f) { return (bf16)(cvt_pk_bf16(f, f) & 0xffffu); }
; __device__ __forceinline__ void phase_ssd(const Params& P, int seg, unsigned char* smem) {
;     ...
;                       for (int j = 0; j < 4; ++j) { const int si0 = (2 * t) * 16 + fq * 4 + j, si1 = si0 + 16;
;                           const float e0 = s0[j] * __expf(fminf(acl_fr - a0[j], 0.f)), e1 = s1[j] * __expf(fminf(acl_fr - a1[j], 0.f));
;                           m[j] = (si0 <= lrow) ? e0 : 0.f; m[4 + j] = (si1 <= lrow) ? e1 : 0.f; } }
;                     v4u mp; mp.x = cvt_pk_bf16(m[0], m[1]); mp.y = cvt_pk_bf16(m[2], m[3]); mp.z = cvt_pk_bf16(m[4], m[5]); mp.w = cvt_pk_bf16(m[6], m[7]);
;                     asm volatile("s_waitcnt lgkmcnt(0)" : "+v"(xb0), "+v"(xb1) :: "memory");
;                     yo = mfma16(__builtin_bit_cast(bf16x8, mp), mk8(xb0, xb1), yo);
;                 }
;             }
; #pragma unroll
;             for (int j = 0; j < 4; ++j) { const int l = lt * 16 + fq * 4 + j, p = pt * 16 + fr; const float xv = bf2f(*(const bf16*)(sb + T_XS + l * 64 + p * 2)), zv = bf2f(*(const bf16*)(sb + T_ZS + l * 64 + p * 2));
;                 ypre[(size_t)(row0 + l) * DINNER + h * 64 + ph * 32 + p] = f2bfh((yo[j] + Dh * xv) * siluf_(zv)); }
;             { v2u xa[2][2][2], bb[2][2];
; #pragma unroll
;               for (int kk = 0; kk < 2; ++kk) {
; #pragma unroll
;                   for (int hh = 0; hh < 2; ++hh) { const int r = kk * 32 + 8 * fq + 4 * hh + tq;
;                       TR_ISSUE(bb[kk][hh], lds0 + par * T_BUF + T_BS + r * 272 + (w * 16 + 4 * tp) * 2);
; #pragma unroll
;                       for (int p2 = 0; p2 < 2; ++p2) TR_ISSUE(xa[p2][kk][hh], lds0 + par * T_BUF + T_XE + r * 80 + (p2 * 16 + 4 * tp) * 2); } }
;               asm volatile("s_waitcnt lgkmcnt(0)" : "+v"(xa[0][0][0]), "+v"(xa[0][0][1]), "+v"(xa[0][1][0]), "+v"(xa[0][1][1]), "+v"(xa[1][0][0]), "+v"(xa[1][0][1]), "+v"(xa[1][1][0]), "+v"(xa[1][1][1]),
;                            "+v"(bb[0][0]), "+v"(bb[0][1]), "+v"(bb[1][0]), "+v"(bb[1][1]) :: "memory");
; #pragma unroll
;               for (int p2 = 0; p2 < 2; ++p2) { st[p2] *= dec;
; #pragma unroll
;                   for (int kk = 0; kk < 2; ++kk) st[p2] = mfma16(mk8(xa[p2][kk][0], xa[p2][kk][1]), mk8(bb[kk][0], bb[kk][1]), st[p2]); } }
; #pragma unroll
;             for (int p2 = 0; p2 < 2; ++p2)
; #pragma unroll
	v_cvt_pk_bf16_f32 v145, v18, v19
	v_cvt_pk_bf16_f32 v146, v20, v21
	v_sub_f32_e32 v156, v137, v136
	v_cvt_pk_bf16_f32 v147, v22, v23
	ds_write_b64 v211, v[140:141] offset:8192
	v_mul_f32_e32 v156, 0x3fb8aa3b, v156
	ds_write_b64 v211, v[142:143] offset:12288
	ds_write_b64 v212, v[144:145] offset:8192
	v_exp_f32_e32 v156, v156
	ds_write_b64 v212, v[146:147] offset:12288
	s_waitcnt lgkmcnt(4)
	v_lshlrev_b32_e32 v112, 16, v126
	v_lshlrev_b32_e32 v152, 16, v132
	v_and_b32_e32 v113, 0xffff0000, v126
	v_lshlrev_b32_e32 v114, 16, v127
	v_and_b32_e32 v153, 0xffff0000, v132
	v_and_b32_e32 v115, 0xffff0000, v127
	v_lshlrev_b32_e32 v154, 16, v133
	v_mul_f32_e32 v120, 0xbfb8aa3b, v112
	v_mul_f32_e32 v121, 0xbfb8aa3b, v113
	v_and_b32_e32 v155, 0xffff0000, v133
	v_mul_f32_e32 v122, 0xbfb8aa3b, v114
	v_mul_f32_e32 v123, 0xbfb8aa3b, v115
	v_mul_f32_e32 v152, v152, v118
	v_exp_f32_e32 v120, v120
	v_exp_f32_e32 v121, v121
	v_mul_f32_e32 v153, v153, v118
	v_exp_f32_e32 v122, v122
	v_exp_f32_e32 v123, v123
	v_mul_f32_e32 v154, v154, v118
	v_add_f32_e32 v120, 1.0, v120
	v_add_f32_e32 v121, 1.0, v121
	v_mul_f32_e32 v155, v155, v118
	v_add_f32_e32 v122, 1.0, v122
	v_add_f32_e32 v123, 1.0, v123
	v_cvt_pk_bf16_f32 v158, v152, v153
	v_rcp_f32_e32 v120, v120
	v_rcp_f32_e32 v121, v121
	v_cvt_pk_bf16_f32 v159, v154, v155
	v_rcp_f32_e32 v122, v122
	v_rcp_f32_e32 v123, v123
	ds_write_b64 v174, v[158:159] offset:32768
	v_mul_f32_e32 v112, v120, v112
	v_mul_f32_e32 v113, v121, v113
	v_mul_f32_e32 v152, v152, v156
	v_mul_f32_e32 v114, v122, v114
	v_mul_f32_e32 v115, v123, v115
	v_mul_f32_e32 v153, v153, v156
	v_lshlrev_b32_e32 v120, 16, v124
	v_mul_f32_e32 v154, v154, v156
	v_and_b32_e32 v121, 0xffff0000, v124
	v_lshlrev_b32_e32 v122, 16, v125
	v_mul_f32_e32 v155, v155, v156
	v_and_b32_e32 v123, 0xffff0000, v125
	v_sub_f32_e32 v140, v151, v96
	v_cvt_pk_bf16_f32 v148, v152, v153
	v_sub_f32_e32 v141, v151, v97
	v_sub_f32_e32 v142, v151, v98
	v_cvt_pk_bf16_f32 v149, v154, v155
	v_sub_f32_e32 v143, v151, v99
	v_exp_f32_e32 v140, v140
	ds_write_b64 v174, v[148:149] offset:37888
	v_exp_f32_e32 v141, v141
	v_exp_f32_e32 v142, v142
	ds_write_b64 v185, v[132:133] offset:43008
	v_exp_f32_e32 v143, v143
	v_mul_f32_e32 v140, v48, v140
	ds_write_b64 v185, v[134:135] offset:47616
	v_mul_f32_e32 v141, v49, v141
	v_mul_f32_e32 v142, v50, v142
	v_mul_f32_e32 v157, 0x3fb8aa3b, v136
	v_mul_f32_e32 v143, v51, v143
	v_cndmask_b32_e64 v140, 0, v140, s[14:15]
	ds_write_b32 v186, v157 offset:256
	v_cndmask_b32_e64 v141, 0, v141, s[16:17]
	v_cndmask_b32_e64 v142, 0, v142, s[22:23]
	v_mul_f32_e32 v150, 0x3fb8aa3b, v137
	v_cndmask_b32_e64 v143, 0, v143, s[34:35]
	v_cvt_pk_bf16_f32 v128, v140, v141
	v_exp_f32_e32 v150, v150
	v_cvt_pk_bf16_f32 v129, v142, v143
	v_mov_b32_e32 v130, 0
	v_mov_b32_e32 v131, 0
	s_nop 1
	v_mfma_f32_16x16x32_bf16 v[24:27], v[56:59], v[128:131], v[24:27]
	s_mul_i32 s65, s56, 0x2000
	s_add_u32 s65, s65, 0x304f1000
	s_add_u32 s48, s0, s65
	s_addc_u32 s49, s1, 0
	s_nop 3
	v_fma_f32 v140, s61, v120, v24
	v_fma_f32 v141, s61, v121, v25
	v_fma_f32 v142, s61, v122, v26
	v_fma_f32 v143, s61, v123, v27
	v_mul_f32_e32 v140, v140, v112
	v_mul_f32_e32 v141, v141, v113
	v_mul_f32_e32 v142, v142, v114
	v_mul_f32_e32 v143, v143, v115
	v_cvt_pk_bf16_f32 v138, v140, v141
	v_cvt_pk_bf16_f32 v139, v142, v143
	global_store_dwordx2 v167, v[138:139], s[48:49]
	s_add_u32 s65, s54, 1
	s_sub_u32 s65, s65, s60
	s_lshl_b32 s65, s65, 6
	s_add_u32 s56, s65, s20
	s_waitcnt lgkmcnt(0)
	s_barrier
	s_mov_b32 s80, s77
	s_mov_b32 s77, s78
	s_mov_b32 s78, s79
	s_mov_b32 s79, s80
	s_mov_b32 s80, s82
	s_mov_b32 s82, s83
	s_mov_b32 s83, s84
	s_mov_b32 s84, s80
	s_mov_b32 s80, s85
	s_mov_b32 s85, s86
	s_mov_b32 s86, s87
	s_mov_b32 s87, s80
	s_add_u32 s54, s54, 1
	s_cmp_ge_u32 s54, s39
	s_cbranch_scc1 .Lssd_done
	v_add_u32_e32 v213, s77, v187
	v_add_u32_e32 v214, s77, v188
	v_add_u32_e32 v215, s77, v189
	v_add_u32_e32 v216, s77, v190
	v_add_u32_e32 v217, s77, v207
	v_add_u32_e32 v218, s77, v208
	v_add_u32_e32 v221, s82, v187
	v_add_u32_e32 v222, s82, v188
	v_add_u32_e32 v223, s82, v189
	v_add_u32_e32 v224, s82, v190
	ds_read_b128 v[28:31], v221
	ds_read_b128 v[32:35], v222
	ds_read_b128 v[40:43], v223
	ds_read_b128 v[44:47], v224
	ds_read_b128 v[48:51], v195 offset:8192
	ds_read_b128 v[52:55], v196 offset:8192
	ds_read_b128 v[56:59], v197 offset:8192
	ds_read_b128 v[60:63], v198 offset:8192
	ds_read_b32 v151, v199 offset:256
	ds_read_b64_tr_b16 v[96:97], v217
	ds_read_b64_tr_b16 v[98:99], v217 offset:4096
	ds_read_b64_tr_b16 v[100:101], v217 offset:8192
	ds_read_b64_tr_b16 v[102:103], v217 offset:12288
	ds_read_b64_tr_b16 v[104:105], v218
	ds_read_b64_tr_b16 v[106:107], v218 offset:4096
	s_waitcnt lgkmcnt(11)
	ds_read_b64_tr_b16 v[108:109], v218 offset:8192
	ds_read_b64_tr_b16 v[110:111], v218 offset:12288
	ds_read_b64_tr_b16 v[112:113], v206 offset:37888
	ds_read_b64_tr_b16 v[114:115], v206 offset:39168
	s_waitcnt lgkmcnt(11)
	ds_read_b64_tr_b16 v[124:125], v206 offset:37920
	ds_read_b64_tr_b16 v[126:127], v206 offset:39200
	ds_read_b64_tr_b16 v[120:121], v206 offset:40448
	ds_read_b64_tr_b16 v[122:123], v206 offset:41728
	s_add_u32 m0, s84, s81
	s_nop 0
	global_load_lds_dwordx4 v225, s[40:41]
	s_waitcnt lgkmcnt(11)
	ds_read_b64_tr_b16 v[128:129], v206 offset:40480
	ds_read_b64_tr_b16 v[130:131], v206 offset:41760
	ds_read_b128 v[64:67], v213
	ds_read_b128 v[68:71], v214
	s_waitcnt lgkmcnt(11)
; __device__ __forceinline__ void phase_ssd(const Params& P, int seg, unsigned char* smem) {
;     ...
;             bf16x8 cf[4];
; #pragma unroll
;             for (int k = 0; k < 4; ++k) cf[k] = *(const bf16x8*)(sb + T_CS + (lt * 16 + fr) * 272 + (k * 32 + fq * 8) * 2);
;             f32x4 yo = {0.f, 0.f, 0.f, 0.f};
; #pragma unroll
;             for (int k = 0; k < 4; ++k) { const bf16x8 bb = *(const bf16x8*)((const unsigned char*)StR + (pt * 16 + fr) * 272 + (k * 32 + fq * 8) * 2); yo = mfma16(cf[k], bb, yo); }
; { const f32x4 a4 = *(const f32x4*)(acP + lt * 16 + fq * 4);
; #pragma unroll
;               for (int j = 0; j < 4; ++j) yo[j] *= __expf(a4[j]); }
;             const float acl_fr = acP[lt * 16 + fr]; const int lrow = lt * 16 + fr;
; #pragma unroll
;             for (int t = 0; t < 2; ++t) {
;                 if (2 * t <= lt) {
;                     v2u xb0, xb1;
;                     { const unsigned a0 = lds0 + par * T_BUF + T_XD + (32 * t + 4 * fq + tq) * 80 + (pt * 16 + 4 * tp) * 2, a1 = a0 + 16 * 80; TR_ISSUE(xb0, a0); TR_ISSUE(xb1, a1); }
;                     float m[8];
;                     { f32x4 s0 = {0.f, 0.f, 0.f, 0.f}, s1 = {0.f, 0.f, 0.f, 0.f};
; #pragma unroll
;                       for (int k = 0; k < 4; ++k) { const bf16x8 bf0 = *(const bf16x8*)(sb + T_BS + ((2 * t) * 16 + fr) * 272 + (k * 32 + fq * 8) * 2), bf1 = *(const bf16x8*)(sb + T_BS + ((2 * t + 1) * 16 + fr) * 272 + (k * 32 + fq * 8) * 2);
;                           s0 = mfma16(bf0, cf[k], s0); s1 = mfma16(bf1, cf[k], s1); }
;                       const f32x4 a0 = *(const f32x4*)(acP + (2 * t) * 16 + fq * 4), a1 = *(const f32x4*)(acP + (2 * t + 1) * 16 + fq * 4);
; #pragma unroll
;                       for (int j = 0; j < 4; ++j) { const int si0 = (2 * t) * 16 + fq * 4 + j, si1 = si0 + 16;
;                           const float e0 = s0[j] * __expf(fminf(acl_fr - a0[j], 0.f)), e1 = s1[j] * __expf(fminf(acl_fr - a1[j], 0.f));
;                           m[j] = (si0 <= lrow) ? e0 : 0.f; m[4 + j] = (si1 <= lrow) ? e1 : 0.f; } }
;                     v4u mp; mp.x = cvt_pk_bf16(m[0], m[1]); mp.y = cvt_pk_bf16(m[2], m[3]); mp.z = cvt_pk_bf16(m[4], m[5]); mp.w = cvt_pk_bf16(m[6], m[7]);
;                     asm volatile("s_waitcnt lgkmcnt(0)" : "+v"(xb0), "+v"(xb1) :: "memory");
;                     yo = mfma16(__builtin_bit_cast(bf16x8, mp), mk8(xb0, xb1), yo);
	ds_read_b128 v[72:75], v215
	s_add_u32 m0, s87, s81
	s_nop 0
	global_load_lds_dwordx4 v226, s[40:41]
	ds_read_b128 v[76:79], v216
	v_mfma_f32_16x16x32_bf16 v[24:27], v[48:51], v[28:31], 0
	v_mfma_f32_16x16x32_bf16 v[24:27], v[52:55], v[32:35], v[24:27]
	v_mfma_f32_16x16x32_bf16 v[24:27], v[56:59], v[40:43], v[24:27]
	v_mfma_f32_16x16x32_bf16 v[24:27], v[60:63], v[44:47], v[24:27]
	ds_read_b64_tr_b16 v[56:57], v202 offset:32768
	s_add_u32 m0, s79, s81
	s_nop 0
	global_load_lds_dwordx4 v219, s[40:41]
	ds_read_b64_tr_b16 v[58:59], v202 offset:34048
	v_mul_f32_e32 v8, v8, v150
	v_mul_f32_e32 v9, v9, v150
	v_mul_f32_e32 v10, v10, v150
	v_mul_f32_e32 v11, v11, v150
	v_mul_f32_e32 v12, v12, v150
	s_add_u32 m0, m0, 0x2000
	s_nop 0
	global_load_lds_dwordx4 v220, s[40:41]
	v_mul_f32_e32 v13, v13, v150
	v_mul_f32_e32 v14, v14, v150
	v_mul_f32_e32 v15, v15, v150
	v_mul_f32_e32 v16, v16, v150
	v_mul_f32_e32 v17, v17, v150
	global_load_dwordx2 v[132:133], v163, s[40:41]
	v_mul_f32_e32 v18, v18, v150
	v_mul_f32_e32 v19, v19, v150
	v_mul_f32_e32 v20, v20, v150
	v_mul_f32_e32 v21, v21, v150
	v_mul_f32_e32 v22, v22, v150
	v_mul_f32_e32 v23, v23, v150
	global_load_dwordx2 v[134:135], v164, s[42:43] nt
	s_waitcnt lgkmcnt(12)
	v_mfma_f32_16x16x32_bf16 v[8:11], v[96:99], v[112:115], v[8:11]
	s_waitcnt lgkmcnt(10)
	v_mfma_f32_16x16x32_bf16 v[12:15], v[96:99], v[124:127], v[12:15]
	v_mfma_f32_16x16x32_bf16 v[16:19], v[104:107], v[112:115], v[16:19]
	v_mfma_f32_16x16x32_bf16 v[20:23], v[104:107], v[124:127], v[20:23]
	s_waitcnt lgkmcnt(8)
	v_mfma_f32_16x16x32_bf16 v[8:11], v[100:103], v[120:123], v[8:11]
	s_waitcnt lgkmcnt(6)
	v_mfma_f32_16x16x32_bf16 v[12:15], v[100:103], v[128:131], v[12:15]
	global_load_dword v118, v165, s[44:45]
	v_mfma_f32_16x16x32_bf16 v[16:19], v[108:111], v[120:123], v[16:19]
	v_mfma_f32_16x16x32_bf16 v[20:23], v[108:111], v[128:131], v[20:23]
	ds_read_b128 v[96:99], v200 offset:256
	ds_read_b64 v[124:125], v204 offset:43008
	ds_read_b64 v[126:127], v204 offset:47616
	s_waitcnt lgkmcnt(8)
	v_mfma_f32_16x16x32_bf16 v[48:51], v[64:67], v[28:31], 0
	global_load_dword v136, v165, s[46:47]
	s_waitcnt lgkmcnt(7)
	v_mfma_f32_16x16x32_bf16 v[48:51], v[68:71], v[32:35], v[48:51]
	s_waitcnt lgkmcnt(6)
	v_mfma_f32_16x16x32_bf16 v[48:51], v[72:75], v[40:43], v[48:51]
	s_waitcnt lgkmcnt(5)
	v_mfma_f32_16x16x32_bf16 v[48:51], v[76:79], v[44:47], v[48:51]
	v_exp_f32_e32 v160, v151
	s_nop 0
	v_mul_f32_e32 v24, v24, v160
	global_load_dword v137, v166, s[46:47]
	v_mul_f32_e32 v25, v25, v160
	v_mul_f32_e32 v26, v26, v160
	v_mul_f32_e32 v27, v27, v160
	v_cvt_pk_bf16_f32 v140, v8, v9
	v_cvt_pk_bf16_f32 v141, v10, v11
	v_cvt_pk_bf16_f32 v142, v12, v13
	s_add_u32 s66, s54, 3
	s_cmp_lt_u32 s66, s39
	s_cselect_b32 s74, 0xc0000, 0
	s_cselect_b32 s75, 0x280000, 0
	s_cselect_b32 s76, 0x4000, 0
	s_add_u32 s40, s40, s74
	s_addc_u32 s41, s41, 0
	s_add_u32 s42, s42, s75
	s_addc_u32 s43, s43, 0
	s_add_u32 s44, s44, s76
	s_addc_u32 s45, s45, 0
	s_add_u32 s46, s46, s76
	s_addc_u32 s47, s47, 0
	v_cvt_pk_bf16_f32 v143, v14, v15
	v_cvt_pk_bf16_f32 v144, v16, v17
	s_waitcnt vmcnt(10)
	v_cvt_pk_bf16_f32 v145, v18, v19
	v_cvt_pk_bf16_f32 v146, v20, v21
	v_sub_f32_e32 v156, v117, v116
	v_cvt_pk_bf16_f32 v147, v22, v23
	ds_write_b64 v211, v[140:141]
	v_mul_f32_e32 v156, 0x3fb8aa3b, v156
	ds_write_b64 v211, v[142:143] offset:4096
	ds_write_b64 v212, v[144:145]
	v_exp_f32_e32 v156, v156
	ds_write_b64 v212, v[146:147] offset:4096
	s_waitcnt lgkmcnt(4)
	v_lshlrev_b32_e32 v112, 16, v126
	v_lshlrev_b32_e32 v152, 16, v4
	v_and_b32_e32 v113, 0xffff0000, v126
	v_lshlrev_b32_e32 v114, 16, v127
	v_and_b32_e32 v153, 0xffff0000, v4
	v_and_b32_e32 v115, 0xffff0000, v127
	v_lshlrev_b32_e32 v154, 16, v5
	v_mul_f32_e32 v120, 0xbfb8aa3b, v112
	v_mul_f32_e32 v121, 0xbfb8aa3b, v113
	v_and_b32_e32 v155, 0xffff0000, v5
	v_mul_f32_e32 v122, 0xbfb8aa3b, v114
	v_mul_f32_e32 v123, 0xbfb8aa3b, v115
	v_mul_f32_e32 v152, v152, v6
	v_exp_f32_e32 v120, v120
	v_exp_f32_e32 v121, v121
	v_mul_f32_e32 v153, v153, v6
	v_exp_f32_e32 v122, v122
	v_exp_f32_e32 v123, v123
	v_mul_f32_e32 v154, v154, v6
	v_add_f32_e32 v120, 1.0, v120
	v_add_f32_e32 v121, 1.0, v121
	v_mul_f32_e32 v155, v155, v6
	v_add_f32_e32 v122, 1.0, v122
	v_add_f32_e32 v123, 1.0, v123
	v_cvt_pk_bf16_f32 v158, v152, v153
	v_rcp_f32_e32 v120, v120
	v_rcp_f32_e32 v121, v121
	v_cvt_pk_bf16_f32 v159, v154, v155
	v_rcp_f32_e32 v122, v122
	v_rcp_f32_e32 v123, v123
	ds_write_b64 v171, v[158:159] offset:32768
	v_mul_f32_e32 v112, v120, v112
	v_mul_f32_e32 v113, v121, v113
	v_mul_f32_e32 v152, v152, v156
	v_mul_f32_e32 v114, v122, v114
	v_mul_f32_e32 v115, v123, v115
	v_mul_f32_e32 v153, v153, v156
	v_lshlrev_b32_e32 v120, 16, v124
	v_mul_f32_e32 v154, v154, v156
	v_and_b32_e32 v121, 0xffff0000, v124
	v_lshlrev_b32_e32 v122, 16, v125
	v_mul_f32_e32 v155, v155, v156
	v_and_b32_e32 v123, 0xffff0000, v125
	v_sub_f32_e32 v140, v151, v96
	v_cvt_pk_bf16_f32 v148, v152, v153
	v_sub_f32_e32 v141, v151, v97
	v_sub_f32_e32 v142, v151, v98
	v_cvt_pk_bf16_f32 v149, v154, v155
	v_sub_f32_e32 v143, v151, v99
	v_exp_f32_e32 v140, v140
	ds_write_b64 v171, v[148:149] offset:37888
	v_exp_f32_e32 v141, v141
	v_exp_f32_e32 v142, v142
	ds_write_b64 v184, v[4:5] offset:43008
	v_exp_f32_e32 v143, v143
	v_mul_f32_e32 v140, v48, v140
	ds_write_b64 v184, v[36:37] offset:47616
	v_mul_f32_e32 v141, v49, v141
	v_mul_f32_e32 v142, v50, v142
	v_mul_f32_e32 v157, 0x3fb8aa3b, v116
	v_mul_f32_e32 v143, v51, v143
	v_cndmask_b32_e64 v140, 0, v140, s[14:15]
	ds_write_b32 v186, v157
	v_cndmask_b32_e64 v141, 0, v141, s[16:17]
	v_cndmask_b32_e64 v142, 0, v142, s[22:23]
	v_mul_f32_e32 v150, 0x3fb8aa3b, v117
	v_cndmask_b32_e64 v143, 0, v143, s[34:35]
	v_cvt_pk_bf16_f32 v128, v140, v141
	v_exp_f32_e32 v150, v150
	v_cvt_pk_bf16_f32 v129, v142, v143
	v_mov_b32_e32 v130, 0
	v_mov_b32_e32 v131, 0
	s_nop 1
	v_mfma_f32_16x16x32_bf16 v[24:27], v[56:59], v[128:131], v[24:27]
	s_mul_i32 s65, s56, 0x2000
	s_add_u32 s65, s65, 0x304f1000
	s_add_u32 s48, s0, s65
	s_addc_u32 s49, s1, 0
	s_nop 3
	v_fma_f32 v140, s61, v120, v24
	v_fma_f32 v141, s61, v121, v25
	v_fma_f32 v142, s61, v122, v26
	v_fma_f32 v143, s61, v123, v27
	v_mul_f32_e32 v140, v140, v112
	v_mul_f32_e32 v141, v141, v113
	v_mul_f32_e32 v142, v142, v114
	v_mul_f32_e32 v143, v143, v115
	v_cvt_pk_bf16_f32 v138, v140, v141
	v_cvt_pk_bf16_f32 v139, v142, v143
	global_store_dwordx2 v167, v[138:139], s[48:49]
	s_add_u32 s65, s54, 1
	s_sub_u32 s65, s65, s60
	s_lshl_b32 s65, s65, 6
	s_add_u32 s56, s65, s20
	s_waitcnt lgkmcnt(0)
	s_barrier
	s_mov_b32 s80, s77
	s_mov_b32 s77, s78
	s_mov_b32 s78, s79
	s_mov_b32 s79, s80
	s_mov_b32 s80, s82
	s_mov_b32 s82, s83
	s_mov_b32 s83, s84
	s_mov_b32 s84, s80
	s_mov_b32 s80, s85
	s_mov_b32 s85, s86
	s_mov_b32 s86, s87
	s_mov_b32 s87, s80
	s_add_u32 s54, s54, 1
	s_cmp_lt_u32 s54, s39
	s_cbranch_scc1 .Lssd_loop0
	s_branch .Lssd_done
; __device__ __forceinline__ void phase_ssd(const Params& P, int seg, unsigned char* smem) {
;     ...
;             bf16x8 cf[4];
; #pragma unroll
;             for (int k = 0; k < 4; ++k) cf[k] = *(const bf16x8*)(sb + T_CS + (lt * 16 + fr) * 272 + (k * 32 + fq * 8) * 2);
;             f32x4 yo = {0.f, 0.f, 0.f, 0.f};
; #pragma unroll
;             for (int k = 0; k < 4; ++k) { const bf16x8 bb = *(const bf16x8*)((const unsigned char*)StR + (pt * 16 + fr) * 272 + (k * 32 + fq * 8) * 2); yo = mfma16(cf[k], bb, yo); }
; { const f32x4 a4 = *(const f32x4*)(acP + lt * 16 + fq * 4);
; #pragma unroll
;               for (int j = 0; j < 4; ++j) yo[j] *= __expf(a4[j]); }
;             const float acl_fr = acP[lt * 16 + fr]; const int lrow = lt * 16 + fr;
; #pragma unroll
;             for (int t = 0; t < 2; ++t) {
;                 if (2 * t <= lt) {
;                     v2u xb0, xb1;
;                     { const unsigned a0 = lds0 + par * T_BUF + T_XD + (32 * t + 4 * fq + tq) * 80 + (pt * 16 + 4 * tp) * 2, a1 = a0 + 16 * 80; TR_ISSUE(xb0, a0); TR_ISSUE(xb1, a1); }
;                     float m[8];
;                     { f32x4 s0 = {0.f, 0.f, 0.f, 0.f}, s1 = {0.f, 0.f, 0.f, 0.f};
; #pragma unroll
;                       for (int k = 0; k < 4; ++k) { const bf16x8 bf0 = *(const bf16x8*)(sb + T_BS + ((2 * t) * 16 + fr) * 272 + (k * 32 + fq * 8) * 2), bf1 = *(const bf16x8*)(sb + T_BS + ((2 * t + 1) * 16 + fr) * 272 + (k * 32 + fq * 8) * 2);
;                           s0 = mfma16(bf0, cf[k], s0); s1 = mfma16(bf1, cf[k], s1); }
;                       const f32x4 a0 = *(const f32x4*)(acP + (2 * t) * 16 + fq * 4), a1 = *(const f32x4*)(acP + (2 * t + 1) * 16 + fq * 4);
; #pragma unroll
;                       for (int j = 0; j < 4; ++j) { const int si0 = (2 * t) * 16 + fq * 4 + j, si1 = si0 + 16;
;                           const float e0 = s0[j] * __expf(fminf(acl_fr - a0[j], 0.f)), e1 = s1[j] * __expf(fminf(acl_fr - a1[j], 0.f));
;                           m[j] = (si0 <= lrow) ? e0 : 0.f; m[4 + j] = (si1 <= lrow) ? e1 : 0.f; } }
;                     v4u mp; mp.x = cvt_pk_bf16(m[0], m[1]); mp.y = cvt_pk_bf16(m[2], m[3]); mp.z = cvt_pk_bf16(m[4], m[5]); mp.w = cvt_pk_bf16(m[6], m[7]);
;                     asm volatile("s_waitcnt lgkmcnt(0)" : "+v"(xb0), "+v"(xb1) :: "memory");
;                     yo = mfma16(__builtin_bit_cast(bf16x8, mp), mk8(xb0, xb1), yo);
.Lssd_loop1:
	v_add_u32_e32 v213, s77, v187
	v_add_u32_e32 v214, s77, v188
	v_add_u32_e32 v215, s77, v189
	v_add_u32_e32 v216, s77, v190
	v_add_u32_e32 v217, s77, v207
	v_add_u32_e32 v218, s77, v208
	v_add_u32_e32 v221, s82, v187
	v_add_u32_e32 v222, s82, v188
	v_add_u32_e32 v223, s82, v189
	v_add_u32_e32 v224, s82, v190
	ds_read_b128 v[28:31], v221 offset:4096
	ds_read_b128 v[32:35], v222 offset:4096
	ds_read_b128 v[40:43], v223 offset:4096
	ds_read_b128 v[44:47], v224 offset:4096
	ds_read_b128 v[48:51], v195
	ds_read_b128 v[52:55], v196
	ds_read_b128 v[56:59], v197
	ds_read_b128 v[60:63], v198
	ds_read_b32 v151, v199 offset:64
	ds_read_b64_tr_b16 v[96:97], v217
	ds_read_b64_tr_b16 v[98:99], v217 offset:4096
	ds_read_b64_tr_b16 v[100:101], v217 offset:8192
	ds_read_b64_tr_b16 v[102:103], v217 offset:12288
	ds_read_b64_tr_b16 v[104:105], v218
	ds_read_b64_tr_b16 v[106:107], v218 offset:4096
	s_waitcnt lgkmcnt(11)
	ds_read_b64_tr_b16 v[108:109], v218 offset:8192
	ds_read_b64_tr_b16 v[110:111], v218 offset:12288
	ds_read_b64_tr_b16 v[112:113], v205 offset:37888
	ds_read_b64_tr_b16 v[114:115], v205 offset:39168
	s_waitcnt lgkmcnt(11)
	ds_read_b64_tr_b16 v[124:125], v205 offset:37920
	ds_read_b64_tr_b16 v[126:127], v205 offset:39200
	ds_read_b64_tr_b16 v[120:121], v205 offset:40448
	ds_read_b64_tr_b16 v[122:123], v205 offset:41728
	s_waitcnt lgkmcnt(11)
	ds_read_b64_tr_b16 v[128:129], v205 offset:40480
	ds_read_b64_tr_b16 v[130:131], v205 offset:41760
	ds_read_b128 v[64:67], v213
	ds_read_b128 v[68:71], v214
	s_add_u32 m0, s84, s81
	s_nop 0
	global_load_lds_dwordx4 v225, s[40:41]
	s_waitcnt lgkmcnt(11)
	ds_read_b128 v[72:75], v215
	ds_read_b128 v[76:79], v216
	ds_read_b128 v[80:83], v213 offset:4096
	ds_read_b128 v[84:87], v214 offset:4096
	s_waitcnt lgkmcnt(11)
	ds_read_b128 v[88:91], v215 offset:4096
	ds_read_b128 v[92:95], v216 offset:4096
	s_add_u32 m0, s87, s81
	s_nop 0
	global_load_lds_dwordx4 v226, s[40:41]
	v_mfma_f32_16x16x32_bf16 v[24:27], v[48:51], v[28:31], 0
	v_mfma_f32_16x16x32_bf16 v[24:27], v[52:55], v[32:35], v[24:27]
	v_mfma_f32_16x16x32_bf16 v[24:27], v[56:59], v[40:43], v[24:27]
	v_mfma_f32_16x16x32_bf16 v[24:27], v[60:63], v[44:47], v[24:27]
	ds_read_b64_tr_b16 v[56:57], v201 offset:32768
	ds_read_b64_tr_b16 v[58:59], v201 offset:34048
	v_mul_f32_e32 v8, v8, v150
	s_add_u32 m0, s79, s81
	s_nop 0
	global_load_lds_dwordx4 v219, s[40:41]
	v_mul_f32_e32 v9, v9, v150
	v_mul_f32_e32 v10, v10, v150
	v_mul_f32_e32 v11, v11, v150
	v_mul_f32_e32 v12, v12, v150
	v_mul_f32_e32 v13, v13, v150
	v_mul_f32_e32 v14, v14, v150
	s_add_u32 m0, m0, 0x2000
	s_nop 0
	global_load_lds_dwordx4 v220, s[40:41]
	v_mul_f32_e32 v15, v15, v150
	v_mul_f32_e32 v16, v16, v150
	v_mul_f32_e32 v17, v17, v150
	v_mul_f32_e32 v18, v18, v150
	v_mul_f32_e32 v19, v19, v150
	v_mul_f32_e32 v20, v20, v150
	v_mul_f32_e32 v21, v21, v150
	global_load_dwordx2 v[4:5], v163, s[40:41]
	v_mul_f32_e32 v22, v22, v150
	v_mul_f32_e32 v23, v23, v150
	v_mfma_f32_16x16x32_bf16 v[8:11], v[96:99], v[112:115], v[8:11]
	s_waitcnt lgkmcnt(14)
	v_mfma_f32_16x16x32_bf16 v[12:15], v[96:99], v[124:127], v[12:15]
	v_mfma_f32_16x16x32_bf16 v[16:19], v[104:107], v[112:115], v[16:19]
	v_mfma_f32_16x16x32_bf16 v[20:23], v[104:107], v[124:127], v[20:23]
	s_waitcnt lgkmcnt(12)
	v_mfma_f32_16x16x32_bf16 v[8:11], v[100:103], v[120:123], v[8:11]
	global_load_dwordx2 v[36:37], v164, s[42:43] nt
	s_waitcnt lgkmcnt(10)
	v_mfma_f32_16x16x32_bf16 v[12:15], v[100:103], v[128:131], v[12:15]
	v_mfma_f32_16x16x32_bf16 v[16:19], v[108:111], v[120:123], v[16:19]
	v_mfma_f32_16x16x32_bf16 v[20:23], v[108:111], v[128:131], v[20:23]
	ds_read_b128 v[96:99], v200
	ds_read_b128 v[100:103], v200 offset:64
	ds_read_b64 v[124:125], v203 offset:44160
	global_load_dword v6, v165, s[44:45]
	ds_read_b64 v[126:127], v203 offset:48768
	s_waitcnt lgkmcnt(13)
	v_mfma_f32_16x16x32_bf16 v[48:51], v[64:67], v[28:31], 0
	s_waitcnt lgkmcnt(9)
	v_mfma_f32_16x16x32_bf16 v[52:55], v[80:83], v[28:31], 0
	v_mfma_f32_16x16x32_bf16 v[48:51], v[68:71], v[32:35], v[48:51]
	s_waitcnt lgkmcnt(8)
	v_mfma_f32_16x16x32_bf16 v[52:55], v[84:87], v[32:35], v[52:55]
	v_mfma_f32_16x16x32_bf16 v[48:51], v[72:75], v[40:43], v[48:51]
	s_waitcnt lgkmcnt(7)
	v_mfma_f32_16x16x32_bf16 v[52:55], v[88:91], v[40:43], v[52:55]
	global_load_dword v116, v165, s[46:47]
	v_mfma_f32_16x16x32_bf16 v[48:51], v[76:79], v[44:47], v[48:51]
	s_waitcnt lgkmcnt(6)
	v_mfma_f32_16x16x32_bf16 v[52:55], v[92:95], v[44:47], v[52:55]
	v_exp_f32_e32 v160, v151
	s_nop 0
	v_mul_f32_e32 v24, v24, v160
	v_mul_f32_e32 v25, v25, v160
	v_mul_f32_e32 v26, v26, v160
	v_mul_f32_e32 v27, v27, v160
	global_load_dword v117, v166, s[46:47]
	v_cvt_pk_bf16_f32 v140, v8, v9
	v_cvt_pk_bf16_f32 v141, v10, v11
	v_cvt_pk_bf16_f32 v142, v12, v13
	v_cvt_pk_bf16_f32 v143, v14, v15
	v_cvt_pk_bf16_f32 v144, v16, v17
	v_cvt_pk_bf16_f32 v145, v18, v19
	s_add_u32 s66, s54, 3
	s_cmp_lt_u32 s66, s39
	s_cselect_b32 s74, 0xc0000, 0
	s_cselect_b32 s75, 0x280000, 0
	s_cselect_b32 s76, 0x4000, 0
	s_add_u32 s40, s40, s74
	s_addc_u32 s41, s41, 0
	s_add_u32 s42, s42, s75
	s_addc_u32 s43, s43, 0
	s_add_u32 s44, s44, s76
	s_addc_u32 s45, s45, 0
	s_add_u32 s46, s46, s76
	s_addc_u32 s47, s47, 0
	v_cvt_pk_bf16_f32 v146, v20, v21
	v_cvt_pk_bf16_f32 v147, v22, v23
	ds_write_b64 v211, v[140:141] offset:8192
	s_waitcnt vmcnt(10)
	ds_write_b64 v211, v[142:143] offset:12288
	ds_write_b64 v212, v[144:145] offset:8192
	v_sub_f32_e32 v156, v137, v136
	ds_write_b64 v212, v[146:147] offset:12288
	s_waitcnt lgkmcnt(4)
; __device__ __forceinline__ bf16 f2bfh(float f) { return (bf16)(cvt_pk_bf16(f, f) & 0xffffu); }
; __device__ __forceinline__ void phase_ssd(const Params& P, int seg, unsigned char* smem) {
;     ...
;                       for (int j = 0; j < 4; ++j) { const int si0 = (2 * t) * 16 + fq * 4 + j, si1 = si0 + 16;
;                           const float e0 = s0[j] * __expf(fminf(acl_fr - a0[j], 0.f)), e1 = s1[j] * __expf(fminf(acl_fr - a1[j], 0.f));
;                           m[j] = (si0 <= lrow) ? e0 : 0.f; m[4 + j] = (si1 <= lrow) ? e1 : 0.f; } }
;                     v4u mp; mp.x = cvt_pk_bf16(m[0], m[1]); mp.y = cvt_pk_bf16(m[2], m[3]); mp.z = cvt_pk_bf16(m[4], m[5]); mp.w = cvt_pk_bf16(m[6], m[7]);
;                     asm volatile("s_waitcnt lgkmcnt(0)" : "+v"(xb0), "+v"(xb1) :: "memory");
;                     yo = mfma16(__builtin_bit_cast(bf16x8, mp), mk8(xb0, xb1), yo);
;                 }
;             }
; #pragma unroll
;             for (int j = 0; j < 4; ++j) { const int l = lt * 16 + fq * 4 + j, p = pt * 16 + fr; const float xv = bf2f(*(const bf16*)(sb + T_XS + l * 64 + p * 2)), zv = bf2f(*(const bf16*)(sb + T_ZS + l * 64 + p * 2));
;                 ypre[(size_t)(row0 + l) * DINNER + h * 64 + ph * 32 + p] = f2bfh((yo[j] + Dh * xv) * siluf_(zv)); }
;             { v2u xa[2][2][2], bb[2][2];
; #pragma unroll
;               for (int kk = 0; kk < 2; ++kk) {
; #pragma unroll
;                   for (int hh = 0; hh < 2; ++hh) { const int r = kk * 32 + 8 * fq + 4 * hh + tq;
;                       TR_ISSUE(bb[kk][hh], lds0 + par * T_BUF + T_BS + r * 272 + (w * 16 + 4 * tp) * 2);
; #pragma unroll
;                       for (int p2 = 0; p2 < 2; ++p2) TR_ISSUE(xa[p2][kk][hh], lds0 + par * T_BUF + T_XE + r * 80 + (p2 * 16 + 4 * tp) * 2); } }
;               asm volatile("s_waitcnt lgkmcnt(0)" : "+v"(xa[0][0][0]), "+v"(xa[0][0][1]), "+v"(xa[0][1][0]), "+v"(xa[0][1][1]), "+v"(xa[1][0][0]), "+v"(xa[1][0][1]), "+v"(xa[1][1][0]), "+v"(xa[1][1][1]),
;                            "+v"(bb[0][0]), "+v"(bb[0][1]), "+v"(bb[1][0]), "+v"(bb[1][1]) :: "memory");
; #pragma unroll
;               for (int p2 = 0; p2 < 2; ++p2) { st[p2] *= dec;
; #pragma unroll
;                   for (int kk = 0; kk < 2; ++kk) st[p2] = mfma16(mk8(xa[p2][kk][0], xa[p2][kk][1]), mk8(bb[kk][0], bb[kk][1]), st[p2]); } }
; #pragma unroll
;             for (int p2 = 0; p2 < 2; ++p2)
; #pragma unroll
	v_lshlrev_b32_e32 v112, 16, v126
	v_mul_f32_e32 v156, 0x3fb8aa3b, v156
	v_and_b32_e32 v113, 0xffff0000, v126
	v_lshlrev_b32_e32 v114, 16, v127
	v_exp_f32_e32 v156, v156
	v_and_b32_e32 v115, 0xffff0000, v127
	v_mul_f32_e32 v120, 0xbfb8aa3b, v112
	v_lshlrev_b32_e32 v152, 16, v132
	v_mul_f32_e32 v121, 0xbfb8aa3b, v113
	v_mul_f32_e32 v122, 0xbfb8aa3b, v114
	v_mul_f32_e32 v123, 0xbfb8aa3b, v115
	v_and_b32_e32 v153, 0xffff0000, v132
	v_exp_f32_e32 v120, v120
	v_exp_f32_e32 v121, v121
	v_lshlrev_b32_e32 v154, 16, v133
	v_exp_f32_e32 v122, v122
	v_exp_f32_e32 v123, v123
	v_and_b32_e32 v155, 0xffff0000, v133
	v_add_f32_e32 v120, 1.0, v120
	v_add_f32_e32 v121, 1.0, v121
	v_mul_f32_e32 v152, v152, v118
	v_add_f32_e32 v122, 1.0, v122
	v_add_f32_e32 v123, 1.0, v123
	v_mul_f32_e32 v153, v153, v118
	v_rcp_f32_e32 v120, v120
	v_rcp_f32_e32 v121, v121
	v_rcp_f32_e32 v122, v122
	v_mul_f32_e32 v154, v154, v118
	v_rcp_f32_e32 v123, v123
	v_mul_f32_e32 v112, v120, v112
	v_mul_f32_e32 v155, v155, v118
	v_mul_f32_e32 v113, v121, v113
	v_mul_f32_e32 v114, v122, v114
	v_cvt_pk_bf16_f32 v158, v152, v153
	v_mul_f32_e32 v115, v123, v115
	v_lshlrev_b32_e32 v120, 16, v124
	v_cvt_pk_bf16_f32 v159, v154, v155
	v_and_b32_e32 v121, 0xffff0000, v124
	v_lshlrev_b32_e32 v122, 16, v125
	v_and_b32_e32 v123, 0xffff0000, v125
	ds_write_b64 v174, v[158:159] offset:32768
	v_sub_f32_e32 v140, v151, v96
	v_sub_f32_e32 v141, v151, v97
	v_mul_f32_e32 v152, v152, v156
	v_sub_f32_e32 v142, v151, v98
	v_sub_f32_e32 v143, v151, v99
	v_mul_f32_e32 v153, v153, v156
	v_exp_f32_e32 v140, v140
	v_exp_f32_e32 v141, v141
	v_mul_f32_e32 v154, v154, v156
	v_exp_f32_e32 v142, v142
	v_exp_f32_e32 v143, v143
	v_mul_f32_e32 v155, v155, v156
	v_mul_f32_e32 v140, v48, v140
	v_mul_f32_e32 v141, v49, v141
	v_mul_f32_e32 v142, v50, v142
	v_cvt_pk_bf16_f32 v148, v152, v153
	v_mul_f32_e32 v143, v51, v143
	v_sub_f32_e32 v144, v151, v100
	v_cvt_pk_bf16_f32 v149, v154, v155
	v_sub_f32_e32 v145, v151, v101
	v_sub_f32_e32 v146, v151, v102
	ds_write_b64 v174, v[148:149] offset:37888
	v_sub_f32_e32 v147, v151, v103
	v_exp_f32_e32 v144, v144
	ds_write_b64 v185, v[132:133] offset:43008
	v_exp_f32_e32 v145, v145
	v_exp_f32_e32 v146, v146
	ds_write_b64 v185, v[134:135] offset:47616
	v_exp_f32_e32 v147, v147
	v_mul_f32_e32 v144, v52, v144
	v_mul_f32_e32 v145, v53, v145
	v_mul_f32_e32 v157, 0x3fb8aa3b, v136
	v_mul_f32_e32 v146, v54, v146
	v_mul_f32_e32 v147, v55, v147
	ds_write_b32 v186, v157 offset:256
	v_cndmask_b32_e64 v144, 0, v144, s[14:15]
	v_cndmask_b32_e64 v145, 0, v145, s[16:17]
	v_mul_f32_e32 v150, 0x3fb8aa3b, v137
	v_cndmask_b32_e64 v146, 0, v146, s[22:23]
	v_cndmask_b32_e64 v147, 0, v147, s[34:35]
	v_exp_f32_e32 v150, v150
	v_cvt_pk_bf16_f32 v128, v140, v141
	v_cvt_pk_bf16_f32 v129, v142, v143
	v_cvt_pk_bf16_f32 v130, v144, v145
	v_cvt_pk_bf16_f32 v131, v146, v147
	s_nop 1
	v_mfma_f32_16x16x32_bf16 v[24:27], v[56:59], v[128:131], v[24:27]
	s_mul_i32 s65, s56, 0x2000
	s_add_u32 s65, s65, 0x304f1000
	s_add_u32 s48, s0, s65
	s_addc_u32 s49, s1, 0
	s_nop 3
	v_fma_f32 v140, s61, v120, v24
	v_fma_f32 v141, s61, v121, v25
	v_fma_f32 v142, s61, v122, v26
	v_fma_f32 v143, s61, v123, v27
	v_mul_f32_e32 v140, v140, v112
	v_mul_f32_e32 v141, v141, v113
	v_mul_f32_e32 v142, v142, v114
	v_mul_f32_e32 v143, v143, v115
	v_cvt_pk_bf16_f32 v138, v140, v141
	v_cvt_pk_bf16_f32 v139, v142, v143
	global_store_dwordx2 v167, v[138:139], s[48:49]
	s_add_u32 s65, s54, 1
	s_sub_u32 s65, s65, s60
	s_lshl_b32 s65, s65, 6
	s_add_u32 s56, s65, s20
	s_waitcnt lgkmcnt(0)
	s_barrier
	s_mov_b32 s80, s77
	s_mov_b32 s77, s78
	s_mov_b32 s78, s79
	s_mov_b32 s79, s80
	s_mov_b32 s80, s82
	s_mov_b32 s82, s83
	s_mov_b32 s83, s84
	s_mov_b32 s84, s80
	s_mov_b32 s80, s85
	s_mov_b32 s85, s86
	s_mov_b32 s86, s87
	s_mov_b32 s87, s80
	s_add_u32 s54, s54, 1
	s_cmp_ge_u32 s54, s39
	s_cbranch_scc1 .Lssd_done
	v_add_u32_e32 v213, s77, v187
	v_add_u32_e32 v214, s77, v188
	v_add_u32_e32 v215, s77, v189
	v_add_u32_e32 v216, s77, v190
	v_add_u32_e32 v217, s77, v207
	v_add_u32_e32 v218, s77, v208
	v_add_u32_e32 v221, s82, v187
	v_add_u32_e32 v222, s82, v188
	v_add_u32_e32 v223, s82, v189
	v_add_u32_e32 v224, s82, v190
	ds_read_b128 v[28:31], v221 offset:4096
	ds_read_b128 v[32:35], v222 offset:4096
	ds_read_b128 v[40:43], v223 offset:4096
	ds_read_b128 v[44:47], v224 offset:4096
	ds_read_b128 v[48:51], v195 offset:8192
	ds_read_b128 v[52:55], v196 offset:8192
	ds_read_b128 v[56:59], v197 offset:8192
	ds_read_b128 v[60:63], v198 offset:8192
	ds_read_b32 v151, v199 offset:320
	ds_read_b64_tr_b16 v[96:97], v217
	ds_read_b64_tr_b16 v[98:99], v217 offset:4096
	ds_read_b64_tr_b16 v[100:101], v217 offset:8192
	ds_read_b64_tr_b16 v[102:103], v217 offset:12288
	ds_read_b64_tr_b16 v[104:105], v218
	ds_read_b64_tr_b16 v[106:107], v218 offset:4096
	s_waitcnt lgkmcnt(11)
	ds_read_b64_tr_b16 v[108:109], v218 offset:8192
	ds_read_b64_tr_b16 v[110:111], v218 offset:12288
	ds_read_b64_tr_b16 v[112:113], v206 offset:37888
	ds_read_b64_tr_b16 v[114:115], v206 offset:39168
	s_waitcnt lgkmcnt(11)
	ds_read_b64_tr_b16 v[124:125], v206 offset:37920
	ds_read_b64_tr_b16 v[126:127], v206 offset:39200
	ds_read_b64_tr_b16 v[120:121], v206 offset:40448
	ds_read_b64_tr_b16 v[122:123], v206 offset:41728
	s_waitcnt lgkmcnt(11)
	ds_read_b64_tr_b16 v[128:129], v206 offset:40480
	ds_read_b64_tr_b16 v[130:131], v206 offset:41760
	ds_read_b128 v[64:67], v213
	ds_read_b128 v[68:71], v214
	s_add_u32 m0, s84, s81
	s_nop 0
	global_load_lds_dwordx4 v225, s[40:41]
	s_waitcnt lgkmcnt(11)
	ds_read_b128 v[72:75], v215
	ds_read_b128 v[76:79], v216
	ds_read_b128 v[80:83], v213 offset:4096
	ds_read_b128 v[84:87], v214 offset:4096
	s_waitcnt lgkmcnt(11)
; __device__ __forceinline__ void phase_ssd(const Params& P, int seg, unsigned char* smem) {
;     ...
;             bf16x8 cf[4];
; #pragma unroll
;             for (int k = 0; k < 4; ++k) cf[k] = *(const bf16x8*)(sb + T_CS + (lt * 16 + fr) * 272 + (k * 32 + fq * 8) * 2);
;             f32x4 yo = {0.f, 0.f, 0.f, 0.f};
; #pragma unroll
;             for (int k = 0; k < 4; ++k) { const bf16x8 bb = *(const bf16x8*)((const unsigned char*)StR + (pt * 16 + fr) * 272 + (k * 32 + fq * 8) * 2); yo = mfma16(cf[k], bb, yo); }
; { const f32x4 a4 = *(const f32x4*)(acP + lt * 16 + fq * 4);
; #pragma unroll
;               for (int j = 0; j < 4; ++j) yo[j] *= __expf(a4[j]); }
;             const float acl_fr = acP[lt * 16 + fr]; const int lrow = lt * 16 + fr;
; #pragma unroll
;             for (int t = 0; t < 2; ++t) {
;                 if (2 * t <= lt) {
;                     v2u xb0, xb1;
;                     { const unsigned a0 = lds0 + par * T_BUF + T_XD + (32 * t + 4 * fq + tq) * 80 + (pt * 16 + 4 * tp) * 2, a1 = a0 + 16 * 80; TR_ISSUE(xb0, a0); TR_ISSUE(xb1, a1); }
;                     float m[8];
;                     { f32x4 s0 = {0.f, 0.f, 0.f, 0.f}, s1 = {0.f, 0.f, 0.f, 0.f};
; #pragma unroll
;                       for (int k = 0; k < 4; ++k) { const bf16x8 bf0 = *(const bf16x8*)(sb + T_BS + ((2 * t) * 16 + fr) * 272 + (k * 32 + fq * 8) * 2), bf1 = *(const bf16x8*)(sb + T_BS + ((2 * t + 1) * 16 + fr) * 272 + (k * 32 + fq * 8) * 2);
;                           s0 = mfma16(bf0, cf[k], s0); s1 = mfma16(bf1, cf[k], s1); }
;                       const f32x4 a0 = *(const f32x4*)(acP + (2 * t) * 16 + fq * 4), a1 = *(const f32x4*)(acP + (2 * t + 1) * 16 + fq * 4);
; #pragma unroll
;                       for (int j = 0; j < 4; ++j) { const int si0 = (2 * t) * 16 + fq * 4 + j, si1 = si0 + 16;
;                           const float e0 = s0[j] * __expf(fminf(acl_fr - a0[j], 0.f)), e1 = s1[j] * __expf(fminf(acl_fr - a1[j], 0.f));
;                           m[j] = (si0 <= lrow) ? e0 : 0.f; m[4 + j] = (si1 <= lrow) ? e1 : 0.f; } }
;                     v4u mp; mp.x = cvt_pk_bf16(m[0], m[1]); mp.y = cvt_pk_bf16(m[2], m[3]); mp.z = cvt_pk_bf16(m[4], m[5]); mp.w = cvt_pk_bf16(m[6], m[7]);
;                     asm volatile("s_waitcnt lgkmcnt(0)" : "+v"(xb0), "+v"(xb1) :: "memory");
;                     yo = mfma16(__builtin_bit_cast(bf16x8, mp), mk8(xb0, xb1), yo);
	ds_read_b128 v[88:91], v215 offset:4096
	ds_read_b128 v[92:95], v216 offset:4096
	s_add_u32 m0, s87, s81
	s_nop 0
	global_load_lds_dwordx4 v226, s[40:41]
	v_mfma_f32_16x16x32_bf16 v[24:27], v[48:51], v[28:31], 0
	v_mfma_f32_16x16x32_bf16 v[24:27], v[52:55], v[32:35], v[24:27]
	v_mfma_f32_16x16x32_bf16 v[24:27], v[56:59], v[40:43], v[24:27]
	v_mfma_f32_16x16x32_bf16 v[24:27], v[60:63], v[44:47], v[24:27]
	ds_read_b64_tr_b16 v[56:57], v202 offset:32768
	ds_read_b64_tr_b16 v[58:59], v202 offset:34048
	v_mul_f32_e32 v8, v8, v150
	s_add_u32 m0, s79, s81
	s_nop 0
	global_load_lds_dwordx4 v219, s[40:41]
	v_mul_f32_e32 v9, v9, v150
	v_mul_f32_e32 v10, v10, v150
	v_mul_f32_e32 v11, v11, v150
	v_mul_f32_e32 v12, v12, v150
	v_mul_f32_e32 v13, v13, v150
	v_mul_f32_e32 v14, v14, v150
	s_add_u32 m0, m0, 0x2000
	s_nop 0
	global_load_lds_dwordx4 v220, s[40:41]
	v_mul_f32_e32 v15, v15, v150
	v_mul_f32_e32 v16, v16, v150
	v_mul_f32_e32 v17, v17, v150
	v_mul_f32_e32 v18, v18, v150
	v_mul_f32_e32 v19, v19, v150
	v_mul_f32_e32 v20, v20, v150
	v_mul_f32_e32 v21, v21, v150
	global_load_dwordx2 v[132:133], v163, s[40:41]
	v_mul_f32_e32 v22, v22, v150
	v_mul_f32_e32 v23, v23, v150
	v_mfma_f32_16x16x32_bf16 v[8:11], v[96:99], v[112:115], v[8:11]
	s_waitcnt lgkmcnt(14)
	v_mfma_f32_16x16x32_bf16 v[12:15], v[96:99], v[124:127], v[12:15]
	v_mfma_f32_16x16x32_bf16 v[16:19], v[104:107], v[112:115], v[16:19]
	v_mfma_f32_16x16x32_bf16 v[20:23], v[104:107], v[124:127], v[20:23]
	s_waitcnt lgkmcnt(12)
	v_mfma_f32_16x16x32_bf16 v[8:11], v[100:103], v[120:123], v[8:11]
	global_load_dwordx2 v[134:135], v164, s[42:43] nt
	s_waitcnt lgkmcnt(10)
	v_mfma_f32_16x16x32_bf16 v[12:15], v[100:103], v[128:131], v[12:15]
	v_mfma_f32_16x16x32_bf16 v[16:19], v[108:111], v[120:123], v[16:19]
	v_mfma_f32_16x16x32_bf16 v[20:23], v[108:111], v[128:131], v[20:23]
	ds_read_b128 v[96:99], v200 offset:256
	ds_read_b128 v[100:103], v200 offset:320
	ds_read_b64 v[124:125], v204 offset:44160
	global_load_dword v118, v165, s[44:45]
	ds_read_b64 v[126:127], v204 offset:48768
	s_waitcnt lgkmcnt(13)
	v_mfma_f32_16x16x32_bf16 v[48:51], v[64:67], v[28:31], 0
	s_waitcnt lgkmcnt(9)
	v_mfma_f32_16x16x32_bf16 v[52:55], v[80:83], v[28:31], 0
	v_mfma_f32_16x16x32_bf16 v[48:51], v[68:71], v[32:35], v[48:51]
	s_waitcnt lgkmcnt(8)
	v_mfma_f32_16x16x32_bf16 v[52:55], v[84:87], v[32:35], v[52:55]
	v_mfma_f32_16x16x32_bf16 v[48:51], v[72:75], v[40:43], v[48:51]
	s_waitcnt lgkmcnt(7)
	v_mfma_f32_16x16x32_bf16 v[52:55], v[88:91], v[40:43], v[52:55]
	global_load_dword v136, v165, s[46:47]
	v_mfma_f32_16x16x32_bf16 v[48:51], v[76:79], v[44:47], v[48:51]
	s_waitcnt lgkmcnt(6)
	v_mfma_f32_16x16x32_bf16 v[52:55], v[92:95], v[44:47], v[52:55]
	v_exp_f32_e32 v160, v151
	s_nop 0
	v_mul_f32_e32 v24, v24, v160
	v_mul_f32_e32 v25, v25, v160
	v_mul_f32_e32 v26, v26, v160
	v_mul_f32_e32 v27, v27, v160
	global_load_dword v137, v166, s[46:47]
	v_cvt_pk_bf16_f32 v140, v8, v9
	v_cvt_pk_bf16_f32 v141, v10, v11
	v_cvt_pk_bf16_f32 v142, v12, v13
	v_cvt_pk_bf16_f32 v143, v14, v15
	v_cvt_pk_bf16_f32 v144, v16, v17
	v_cvt_pk_bf16_f32 v145, v18, v19
	s_add_u32 s66, s54, 3
	s_cmp_lt_u32 s66, s39
	s_cselect_b32 s74, 0xc0000, 0
	s_cselect_b32 s75, 0x280000, 0
	s_cselect_b32 s76, 0x4000, 0
	s_add_u32 s40, s40, s74
	s_addc_u32 s41, s41, 0
	s_add_u32 s42, s42, s75
	s_addc_u32 s43, s43, 0
	s_add_u32 s44, s44, s76
	s_addc_u32 s45, s45, 0
	s_add_u32 s46, s46, s76
	s_addc_u32 s47, s47, 0
	v_cvt_pk_bf16_f32 v146, v20, v21
	v_cvt_pk_bf16_f32 v147, v22, v23
	ds_write_b64 v211, v[140:141]
	s_waitcnt vmcnt(10)
	ds_write_b64 v211, v[142:143] offset:4096
	ds_write_b64 v212, v[144:145]
	v_sub_f32_e32 v156, v117, v116
	ds_write_b64 v212, v[146:147] offset:4096
	s_waitcnt lgkmcnt(4)
	v_lshlrev_b32_e32 v112, 16, v126
	v_mul_f32_e32 v156, 0x3fb8aa3b, v156
	v_and_b32_e32 v113, 0xffff0000, v126
	v_lshlrev_b32_e32 v114, 16, v127
	v_exp_f32_e32 v156, v156
	v_and_b32_e32 v115, 0xffff0000, v127
	v_mul_f32_e32 v120, 0xbfb8aa3b, v112
	v_lshlrev_b32_e32 v152, 16, v4
	v_mul_f32_e32 v121, 0xbfb8aa3b, v113
	v_mul_f32_e32 v122, 0xbfb8aa3b, v114
	v_mul_f32_e32 v123, 0xbfb8aa3b, v115
	v_and_b32_e32 v153, 0xffff0000, v4
	v_exp_f32_e32 v120, v120
	v_exp_f32_e32 v121, v121
	v_lshlrev_b32_e32 v154, 16, v5
	v_exp_f32_e32 v122, v122
	v_exp_f32_e32 v123, v123
	v_and_b32_e32 v155, 0xffff0000, v5
	v_add_f32_e32 v120, 1.0, v120
	v_add_f32_e32 v121, 1.0, v121
	v_mul_f32_e32 v152, v152, v6
	v_add_f32_e32 v122, 1.0, v122
	v_add_f32_e32 v123, 1.0, v123
	v_mul_f32_e32 v153, v153, v6
	v_rcp_f32_e32 v120, v120
	v_rcp_f32_e32 v121, v121
	v_rcp_f32_e32 v122, v122
	v_mul_f32_e32 v154, v154, v6
	v_rcp_f32_e32 v123, v123
	v_mul_f32_e32 v112, v120, v112
	v_mul_f32_e32 v155, v155, v6
	v_mul_f32_e32 v113, v121, v113
	v_mul_f32_e32 v114, v122, v114
	v_cvt_pk_bf16_f32 v158, v152, v153
	v_mul_f32_e32 v115, v123, v115
	v_lshlrev_b32_e32 v120, 16, v124
	v_cvt_pk_bf16_f32 v159, v154, v155
	v_and_b32_e32 v121, 0xffff0000, v124
	v_lshlrev_b32_e32 v122, 16, v125
	v_and_b32_e32 v123, 0xffff0000, v125
	ds_write_b64 v171, v[158:159] offset:32768
	v_sub_f32_e32 v140, v151, v96
	v_sub_f32_e32 v141, v151, v97
	v_mul_f32_e32 v152, v152, v156
	v_sub_f32_e32 v142, v151, v98
	v_sub_f32_e32 v143, v151, v99
	v_mul_f32_e32 v153, v153, v156
	v_exp_f32_e32 v140, v140
	v_exp_f32_e32 v141, v141
	v_mul_f32_e32 v154, v154, v156
	v_exp_f32_e32 v142, v142
	v_exp_f32_e32 v143, v143
	v_mul_f32_e32 v155, v155, v156
	v_mul_f32_e32 v140, v48, v140
	v_mul_f32_e32 v141, v49, v141
	v_mul_f32_e32 v142, v50, v142
	v_cvt_pk_bf16_f32 v148, v152, v153
	v_mul_f32_e32 v143, v51, v143
	v_sub_f32_e32 v144, v151, v100
	v_cvt_pk_bf16_f32 v149, v154, v155
; __device__ __forceinline__ bf16 f2bfh(float f) { return (bf16)(cvt_pk_bf16(f, f) & 0xffffu); }
; __device__ __forceinline__ void phase_ssd(const Params& P, int seg, unsigned char* smem) {
;     ...
;                       for (int j = 0; j < 4; ++j) { const int si0 = (2 * t) * 16 + fq * 4 + j, si1 = si0 + 16;
;                           const float e0 = s0[j] * __expf(fminf(acl_fr - a0[j], 0.f)), e1 = s1[j] * __expf(fminf(acl_fr - a1[j], 0.f));
;                           m[j] = (si0 <= lrow) ? e0 : 0.f; m[4 + j] = (si1 <= lrow) ? e1 : 0.f; } }
;                     v4u mp; mp.x = cvt_pk_bf16(m[0], m[1]); mp.y = cvt_pk_bf16(m[2], m[3]); mp.z = cvt_pk_bf16(m[4], m[5]); mp.w = cvt_pk_bf16(m[6], m[7]);
;                     asm volatile("s_waitcnt lgkmcnt(0)" : "+v"(xb0), "+v"(xb1) :: "memory");
;                     yo = mfma16(__builtin_bit_cast(bf16x8, mp), mk8(xb0, xb1), yo);
;                 }
;             }
; #pragma unroll
;             for (int j = 0; j < 4; ++j) { const int l = lt * 16 + fq * 4 + j, p = pt * 16 + fr; const float xv = bf2f(*(const bf16*)(sb + T_XS + l * 64 + p * 2)), zv = bf2f(*(const bf16*)(sb + T_ZS + l * 64 + p * 2));
;                 ypre[(size_t)(row0 + l) * DINNER + h * 64 + ph * 32 + p] = f2bfh((yo[j] + Dh * xv) * siluf_(zv)); }
;             { v2u xa[2][2][2], bb[2][2];
; #pragma unroll
;               for (int kk = 0; kk < 2; ++kk) {
; #pragma unroll
;                   for (int hh = 0; hh < 2; ++hh) { const int r = kk * 32 + 8 * fq + 4 * hh + tq;
;                       TR_ISSUE(bb[kk][hh], lds0 + par * T_BUF + T_BS + r * 272 + (w * 16 + 4 * tp) * 2);
; #pragma unroll
;                       for (int p2 = 0; p2 < 2; ++p2) TR_ISSUE(xa[p2][kk][hh], lds0 + par * T_BUF + T_XE + r * 80 + (p2 * 16 + 4 * tp) * 2); } }
;               asm volatile("s_waitcnt lgkmcnt(0)" : "+v"(xa[0][0][0]), "+v"(xa[0][0][1]), "+v"(xa[0][1][0]), "+v"(xa[0][1][1]), "+v"(xa[1][0][0]), "+v"(xa[1][0][1]), "+v"(xa[1][1][0]), "+v"(xa[1][1][1]),
;                            "+v"(bb[0][0]), "+v"(bb[0][1]), "+v"(bb[1][0]), "+v"(bb[1][1]) :: "memory");
; #pragma unroll
;               for (int p2 = 0; p2 < 2; ++p2) { st[p2] *= dec;
; #pragma unroll
;                   for (int kk = 0; kk < 2; ++kk) st[p2] = mfma16(mk8(xa[p2][kk][0], xa[p2][kk][1]), mk8(bb[kk][0], bb[kk][1]), st[p2]); } }
; #pragma unroll
;             for (int p2 = 0; p2 < 2; ++p2)
; #pragma unroll
	v_sub_f32_e32 v145, v151, v101
	v_sub_f32_e32 v146, v151, v102
	ds_write_b64 v171, v[148:149] offset:37888
	v_sub_f32_e32 v147, v151, v103
	v_exp_f32_e32 v144, v144
	ds_write_b64 v184, v[4:5] offset:43008
	v_exp_f32_e32 v145, v145
	v_exp_f32_e32 v146, v146
	ds_write_b64 v184, v[36:37] offset:47616
	v_exp_f32_e32 v147, v147
	v_mul_f32_e32 v144, v52, v144
	v_mul_f32_e32 v145, v53, v145
	v_mul_f32_e32 v157, 0x3fb8aa3b, v116
	v_mul_f32_e32 v146, v54, v146
	v_mul_f32_e32 v147, v55, v147
	ds_write_b32 v186, v157
	v_cndmask_b32_e64 v144, 0, v144, s[14:15]
	v_cndmask_b32_e64 v145, 0, v145, s[16:17]
	v_mul_f32_e32 v150, 0x3fb8aa3b, v117
	v_cndmask_b32_e64 v146, 0, v146, s[22:23]
	v_cndmask_b32_e64 v147, 0, v147, s[34:35]
	v_exp_f32_e32 v150, v150
	v_cvt_pk_bf16_f32 v128, v140, v141
	v_cvt_pk_bf16_f32 v129, v142, v143
	v_cvt_pk_bf16_f32 v130, v144, v145
	v_cvt_pk_bf16_f32 v131, v146, v147
	s_nop 1
	v_mfma_f32_16x16x32_bf16 v[24:27], v[56:59], v[128:131], v[24:27]
	s_mul_i32 s65, s56, 0x2000
	s_add_u32 s65, s65, 0x304f1000
	s_add_u32 s48, s0, s65
	s_addc_u32 s49, s1, 0
	s_nop 3
	v_fma_f32 v140, s61, v120, v24
	v_fma_f32 v141, s61, v121, v25
	v_fma_f32 v142, s61, v122, v26
	v_fma_f32 v143, s61, v123, v27
	v_mul_f32_e32 v140, v140, v112
	v_mul_f32_e32 v141, v141, v113
	v_mul_f32_e32 v142, v142, v114
	v_mul_f32_e32 v143, v143, v115
	v_cvt_pk_bf16_f32 v138, v140, v141
	v_cvt_pk_bf16_f32 v139, v142, v143
	global_store_dwordx2 v167, v[138:139], s[48:49]
	s_add_u32 s65, s54, 1
	s_sub_u32 s65, s65, s60
	s_lshl_b32 s65, s65, 6
	s_add_u32 s56, s65, s20
	s_waitcnt lgkmcnt(0)
	s_barrier
	s_mov_b32 s80, s77
	s_mov_b32 s77, s78
	s_mov_b32 s78, s79
	s_mov_b32 s79, s80
	s_mov_b32 s80, s82
	s_mov_b32 s82, s83
	s_mov_b32 s83, s84
	s_mov_b32 s84, s80
	s_mov_b32 s80, s85
	s_mov_b32 s85, s86
	s_mov_b32 s86, s87
	s_mov_b32 s87, s80
	s_add_u32 s54, s54, 1
	s_cmp_lt_u32 s54, s39
	s_cbranch_scc1 .Lssd_loop1
	s_branch .Lssd_done
.Lssd_loop2:
	v_add_u32_e32 v213, s77, v187
	v_add_u32_e32 v214, s77, v188
	v_add_u32_e32 v215, s77, v189
	v_add_u32_e32 v216, s77, v190
	v_add_u32_e32 v221, s85, v187
	v_add_u32_e32 v222, s85, v188
	v_add_u32_e32 v223, s85, v189
	v_add_u32_e32 v224, s85, v190
	ds_read_b128 v[28:31], v221
	ds_read_b128 v[32:35], v222
	ds_read_b128 v[40:43], v223
	ds_read_b128 v[44:47], v224
	ds_read_b128 v[48:51], v195
	ds_read_b128 v[52:55], v196
	ds_read_b128 v[56:59], v197
	ds_read_b128 v[60:63], v198
	ds_read_b32 v151, v199 offset:128
	ds_read_b128 v[64:67], v213
	ds_read_b128 v[68:71], v214
	ds_read_b128 v[72:75], v215
	ds_read_b128 v[76:79], v216
	ds_read_b128 v[80:83], v213 offset:4096
	ds_read_b128 v[84:87], v214 offset:4096
	s_add_u32 m0, s84, s81
	s_nop 0
	global_load_lds_dwordx4 v225, s[40:41]
	s_waitcnt lgkmcnt(11)
	ds_read_b128 v[88:91], v215 offset:4096
	ds_read_b128 v[92:95], v216 offset:4096
	ds_read_b128 v[96:99], v200
	ds_read_b128 v[100:103], v200 offset:64
	s_waitcnt lgkmcnt(11)
	ds_read_b64 v[124:125], v203 offset:45312
	ds_read_b64 v[126:127], v203 offset:49920
	s_add_u32 m0, s87, s81
	s_nop 0
	global_load_lds_dwordx4 v226, s[40:41]
	v_mfma_f32_16x16x32_bf16 v[24:27], v[48:51], v[28:31], 0
	v_mfma_f32_16x16x32_bf16 v[24:27], v[52:55], v[32:35], v[24:27]
	v_mfma_f32_16x16x32_bf16 v[24:27], v[56:59], v[40:43], v[24:27]
	v_mfma_f32_16x16x32_bf16 v[24:27], v[60:63], v[44:47], v[24:27]
	ds_read_b64_tr_b16 v[56:57], v201 offset:32768
	ds_read_b64_tr_b16 v[58:59], v201 offset:34048
	s_add_u32 m0, s79, s81
	s_nop 0
	global_load_lds_dwordx4 v219, s[40:41]
	s_waitcnt lgkmcnt(13)
	v_mfma_f32_16x16x32_bf16 v[48:51], v[64:67], v[28:31], 0
	s_waitcnt lgkmcnt(9)
	v_mfma_f32_16x16x32_bf16 v[52:55], v[80:83], v[28:31], 0
	v_mfma_f32_16x16x32_bf16 v[48:51], v[68:71], v[32:35], v[48:51]
	s_waitcnt lgkmcnt(8)
	v_mfma_f32_16x16x32_bf16 v[52:55], v[84:87], v[32:35], v[52:55]
	v_mfma_f32_16x16x32_bf16 v[48:51], v[72:75], v[40:43], v[48:51]
	s_waitcnt lgkmcnt(7)
	v_mfma_f32_16x16x32_bf16 v[52:55], v[88:91], v[40:43], v[52:55]
	s_add_u32 m0, m0, 0x2000
	s_nop 0
	global_load_lds_dwordx4 v220, s[40:41]
	v_mfma_f32_16x16x32_bf16 v[48:51], v[76:79], v[44:47], v[48:51]
	s_waitcnt lgkmcnt(6)
	v_mfma_f32_16x16x32_bf16 v[52:55], v[92:95], v[44:47], v[52:55]
	ds_read_b128 v[64:67], v213 offset:8192
	ds_read_b128 v[68:71], v214 offset:8192
	ds_read_b128 v[72:75], v215 offset:8192
	ds_read_b128 v[76:79], v216 offset:8192
	global_load_dwordx2 v[4:5], v163, s[40:41]
	ds_read_b64_tr_b16 v[60:61], v201 offset:35328
	ds_read_b64_tr_b16 v[62:63], v201 offset:36608
	v_exp_f32_e32 v160, v151
	s_nop 0
	v_mul_f32_e32 v24, v24, v160
	v_mul_f32_e32 v25, v25, v160
	v_mul_f32_e32 v26, v26, v160
	global_load_dwordx2 v[36:37], v164, s[42:43] nt
	v_mul_f32_e32 v27, v27, v160
	s_waitcnt lgkmcnt(8)
	v_lshlrev_b32_e32 v112, 16, v126
	v_and_b32_e32 v113, 0xffff0000, v126
	v_lshlrev_b32_e32 v114, 16, v127
	v_and_b32_e32 v115, 0xffff0000, v127
	v_mul_f32_e32 v120, 0xbfb8aa3b, v112
	global_load_dword v6, v165, s[44:45]
	v_mul_f32_e32 v121, 0xbfb8aa3b, v113
	v_mul_f32_e32 v122, 0xbfb8aa3b, v114
	v_mul_f32_e32 v123, 0xbfb8aa3b, v115
	v_exp_f32_e32 v120, v120
	v_exp_f32_e32 v121, v121
	v_exp_f32_e32 v122, v122
	global_load_dword v116, v165, s[46:47]
	v_exp_f32_e32 v123, v123
	v_add_f32_e32 v120, 1.0, v120
	v_add_f32_e32 v121, 1.0, v121
	v_add_f32_e32 v122, 1.0, v122
	v_add_f32_e32 v123, 1.0, v123
	v_rcp_f32_e32 v120, v120
	global_load_dword v117, v166, s[46:47]
	v_rcp_f32_e32 v121, v121
	v_rcp_f32_e32 v122, v122
	v_rcp_f32_e32 v123, v123
	v_mul_f32_e32 v112, v120, v112
	v_mul_f32_e32 v113, v121, v113
	v_mul_f32_e32 v114, v122, v114
	s_add_u32 s66, s54, 3
	s_cmp_lt_u32 s66, s39
	s_cselect_b32 s74, 0xc0000, 0
	s_cselect_b32 s75, 0x280000, 0
	s_cselect_b32 s76, 0x4000, 0
	s_add_u32 s40, s40, s74
	s_addc_u32 s41, s41, 0
	s_add_u32 s42, s42, s75
	s_addc_u32 s43, s43, 0
	s_add_u32 s44, s44, s76
	s_addc_u32 s45, s45, 0
	s_add_u32 s46, s46, s76
	s_addc_u32 s47, s47, 0
	v_mul_f32_e32 v115, v123, v115
	v_lshlrev_b32_e32 v120, 16, v124
	s_waitcnt vmcnt(10)
; __device__ __forceinline__ void phase_ssd(const Params& P, int seg, unsigned char* smem) {
;     ...
;         auto load_chunk = [&](int ci, Pre& R) { const int row0 = chunk_row0(ci);
; #pragma unroll
;             for (int i = 0; i < 2; ++i) { const int q = tid + 512 * i, l = q >> 4, c8 = q & 15; const GAS bf16* rp = xconv + (size_t)(row0 + l) * DXBC + g * 128 + c8 * 8;
;                 R.Br[i] = *(const GAS v4u*)(rp + 4096); R.Cr[i] = *(const GAS v4u*)(rp + 5120); }
;             { const int l = tid >> 3, p4 = (tid & 7) * 4; R.Xr = *(const GAS v2u*)(xconv + (size_t)(row0 + l) * DXBC + h * 64 + ph * 32 + p4);
;               R.Zr = __builtin_nontemporal_load((const GAS v2u*)(proj + (size_t)(row0 + l) * NPROJ + OFF_Z + h * 64 + ph * 32 + p4));
;               R.dtl = dtv[(size_t)(row0 + l) * 64 + h]; R.acl = acv[(size_t)(row0 + l) * 64 + h]; }
;             R.alast = acv[(size_t)(row0 + 63) * 64 + h]; R.aclane = acv[(size_t)(row0 + lane) * 64 + h]; };
;         load_chunk(0, RA); if (nchunks > 1) load_chunk(1, RB);
;         auto step = [&](int ci, Pre& R, const int par) {
;             const int row0 = chunk_row0(ci); unsigned char* sb = smem + par * T_BUF; float* acP = acS + par * 64;
;             const bf16* StR = StS + par * (T_STSZ / 2); bf16* StW = StS + (par ^ 1) * (T_STSZ / 2);
;             const float dec = __expf(R.alast);
;             { const float e2 = __expf(R.alast - R.acl);
; #pragma unroll
;               for (int i = 0; i < 2; ++i) { const int q = tid + 512 * i, l = q >> 4, c8 = q & 15; *(v4u*)(sb + T_CS + l * 272 + c8 * 16) = R.Cr[i]; *(v4u*)(sb + T_BS + l * 272 + c8 * 16) = R.Br[i]; }
;               const int l = tid >> 3, p4 = (tid & 7) * 4;
;               const float x0 = bflo(R.Xr.x) * R.dtl, x1 = bfhi(R.Xr.x) * R.dtl, x2 = bflo(R.Xr.y) * R.dtl, x3 = bfhi(R.Xr.y) * R.dtl;
;               v2u d; d.x = cvt_pk_bf16(x0, x1); d.y = cvt_pk_bf16(x2, x3); *(v2u*)(sb + T_XD + l * 80 + p4 * 2) = d;
;               v2u e; e.x = cvt_pk_bf16(x0 * e2, x1 * e2); e.y = cvt_pk_bf16(x2 * e2, x3 * e2); *(v2u*)(sb + T_XE + l * 80 + p4 * 2) = e;
;               *(v2u*)(sb + T_XS + l * 64 + p4 * 2) = R.Xr; *(v2u*)(sb + T_ZS + l * 64 + p4 * 2) = R.Zr;
;               if (w == 0) acP[lane] = R.aclane; }
;             BAR_LDS();
;             if (ci + 2 < nchunks) load_chunk(ci + 2, R);
;             bf16x8 cf[4];
; #pragma unroll
	v_and_b32_e32 v121, 0xffff0000, v124
	v_lshlrev_b32_e32 v122, 16, v125
	v_sub_f32_e32 v156, v137, v136
	v_and_b32_e32 v123, 0xffff0000, v125
	v_sub_f32_e32 v140, v151, v96
	v_mul_f32_e32 v156, 0x3fb8aa3b, v156
	v_sub_f32_e32 v141, v151, v97
	v_sub_f32_e32 v142, v151, v98
	v_exp_f32_e32 v156, v156
	v_sub_f32_e32 v143, v151, v99
	v_exp_f32_e32 v140, v140
	v_lshlrev_b32_e32 v152, 16, v132
	v_exp_f32_e32 v141, v141
	v_exp_f32_e32 v142, v142
	v_and_b32_e32 v153, 0xffff0000, v132
	v_exp_f32_e32 v143, v143
	v_mul_f32_e32 v140, v48, v140
	v_lshlrev_b32_e32 v154, 16, v133
	v_mul_f32_e32 v141, v49, v141
	v_mul_f32_e32 v142, v50, v142
	v_and_b32_e32 v155, 0xffff0000, v133
	v_mul_f32_e32 v143, v51, v143
	v_sub_f32_e32 v144, v151, v100
	v_mul_f32_e32 v152, v152, v118
	v_sub_f32_e32 v145, v151, v101
	v_sub_f32_e32 v146, v151, v102
	v_mul_f32_e32 v153, v153, v118
	v_sub_f32_e32 v147, v151, v103
	v_exp_f32_e32 v144, v144
	v_mul_f32_e32 v154, v154, v118
	v_exp_f32_e32 v145, v145
	v_exp_f32_e32 v146, v146
	v_mul_f32_e32 v155, v155, v118
	v_exp_f32_e32 v147, v147
	v_mul_f32_e32 v144, v52, v144
	v_cvt_pk_bf16_f32 v158, v152, v153
	v_mul_f32_e32 v145, v53, v145
	v_mul_f32_e32 v146, v54, v146
	v_cvt_pk_bf16_f32 v159, v154, v155
	v_mul_f32_e32 v147, v55, v147
	v_cvt_pk_bf16_f32 v128, v140, v141
	ds_write_b64 v174, v[158:159] offset:32768
	v_cvt_pk_bf16_f32 v129, v142, v143
	v_cvt_pk_bf16_f32 v130, v144, v145
	v_mul_f32_e32 v152, v152, v156
	v_cvt_pk_bf16_f32 v131, v146, v147
	s_waitcnt lgkmcnt(7)
	s_nop 0
	v_mfma_f32_16x16x32_bf16 v[24:27], v[56:59], v[128:131], v[24:27]
	v_mul_f32_e32 v153, v153, v156
	ds_read_b128 v[96:99], v200 offset:128
	s_waitcnt lgkmcnt(7)
	v_mfma_f32_16x16x32_bf16 v[48:51], v[64:67], v[28:31], 0
	v_mul_f32_e32 v154, v154, v156
	s_waitcnt lgkmcnt(6)
	v_mfma_f32_16x16x32_bf16 v[48:51], v[68:71], v[32:35], v[48:51]
	s_waitcnt lgkmcnt(5)
	v_mfma_f32_16x16x32_bf16 v[48:51], v[72:75], v[40:43], v[48:51]
	v_mul_f32_e32 v155, v155, v156
	s_waitcnt lgkmcnt(4)
	v_mfma_f32_16x16x32_bf16 v[48:51], v[76:79], v[44:47], v[48:51]
	s_waitcnt lgkmcnt(0)
	v_sub_f32_e32 v140, v151, v96
	v_cvt_pk_bf16_f32 v148, v152, v153
	v_sub_f32_e32 v141, v151, v97
	v_sub_f32_e32 v142, v151, v98
	v_cvt_pk_bf16_f32 v149, v154, v155
	v_sub_f32_e32 v143, v151, v99
	v_exp_f32_e32 v140, v140
	ds_write_b64 v174, v[148:149] offset:37888
	v_exp_f32_e32 v141, v141
	v_exp_f32_e32 v142, v142
	ds_write_b64 v185, v[132:133] offset:43008
	v_exp_f32_e32 v143, v143
	v_mul_f32_e32 v140, v48, v140
	ds_write_b64 v185, v[134:135] offset:47616
	v_mul_f32_e32 v141, v49, v141
	v_mul_f32_e32 v142, v50, v142
	v_mul_f32_e32 v157, 0x3fb8aa3b, v136
	v_mul_f32_e32 v143, v51, v143
	v_cndmask_b32_e64 v140, 0, v140, s[14:15]
	ds_write_b32 v186, v157 offset:256
	v_cndmask_b32_e64 v141, 0, v141, s[16:17]
	v_cndmask_b32_e64 v142, 0, v142, s[22:23]
	v_mul_f32_e32 v150, 0x3fb8aa3b, v137
	v_cndmask_b32_e64 v143, 0, v143, s[34:35]
	v_cvt_pk_bf16_f32 v128, v140, v141
	v_exp_f32_e32 v150, v150
	v_cvt_pk_bf16_f32 v129, v142, v143
	v_mov_b32_e32 v130, 0
	v_mov_b32_e32 v131, 0
	s_nop 1
	v_mfma_f32_16x16x32_bf16 v[24:27], v[60:63], v[128:131], v[24:27]
	s_mul_i32 s65, s56, 0x2000
	s_add_u32 s65, s65, 0x304f1000
	s_add_u32 s48, s0, s65
	s_addc_u32 s49, s1, 0
	s_nop 3
	v_fma_f32 v140, s61, v120, v24
	v_fma_f32 v141, s61, v121, v25
	v_fma_f32 v142, s61, v122, v26
	v_fma_f32 v143, s61, v123, v27
	v_mul_f32_e32 v140, v140, v112
	v_mul_f32_e32 v141, v141, v113
	v_mul_f32_e32 v142, v142, v114
	v_mul_f32_e32 v143, v143, v115
	v_cvt_pk_bf16_f32 v138, v140, v141
	v_cvt_pk_bf16_f32 v139, v142, v143
	global_store_dwordx2 v167, v[138:139], s[48:49]
	s_add_u32 s65, s54, 1
	s_sub_u32 s65, s65, s60
	s_lshl_b32 s65, s65, 6
	s_add_u32 s56, s65, s20
	s_waitcnt lgkmcnt(0)
	s_barrier
	s_mov_b32 s80, s77
	s_mov_b32 s77, s78
	s_mov_b32 s78, s79
	s_mov_b32 s79, s80
	s_mov_b32 s80, s82
	s_mov_b32 s82, s83
	s_mov_b32 s83, s84
	s_mov_b32 s84, s80
	s_mov_b32 s80, s85
	s_mov_b32 s85, s86
	s_mov_b32 s86, s87
	s_mov_b32 s87, s80
	s_add_u32 s54, s54, 1
	s_cmp_ge_u32 s54, s39
	s_cbranch_scc1 .Lssd_done
	v_add_u32_e32 v213, s77, v187
	v_add_u32_e32 v214, s77, v188
	v_add_u32_e32 v215, s77, v189
	v_add_u32_e32 v216, s77, v190
	v_add_u32_e32 v221, s85, v187
	v_add_u32_e32 v222, s85, v188
	v_add_u32_e32 v223, s85, v189
	v_add_u32_e32 v224, s85, v190
	ds_read_b128 v[28:31], v221
	ds_read_b128 v[32:35], v222
	ds_read_b128 v[40:43], v223
	ds_read_b128 v[44:47], v224
	ds_read_b128 v[48:51], v195 offset:8192
	ds_read_b128 v[52:55], v196 offset:8192
	ds_read_b128 v[56:59], v197 offset:8192
	ds_read_b128 v[60:63], v198 offset:8192
	ds_read_b32 v151, v199 offset:384
	ds_read_b128 v[64:67], v213
	ds_read_b128 v[68:71], v214
	ds_read_b128 v[72:75], v215
	ds_read_b128 v[76:79], v216
	ds_read_b128 v[80:83], v213 offset:4096
	ds_read_b128 v[84:87], v214 offset:4096
	s_add_u32 m0, s84, s81
	s_nop 0
	global_load_lds_dwordx4 v225, s[40:41]
	s_waitcnt lgkmcnt(11)
	ds_read_b128 v[88:91], v215 offset:4096
	ds_read_b128 v[92:95], v216 offset:4096
	ds_read_b128 v[96:99], v200 offset:256
	ds_read_b128 v[100:103], v200 offset:320
	s_waitcnt lgkmcnt(11)
	ds_read_b64 v[124:125], v204 offset:45312
	ds_read_b64 v[126:127], v204 offset:49920
	s_add_u32 m0, s87, s81
	s_nop 0
	global_load_lds_dwordx4 v226, s[40:41]
	v_mfma_f32_16x16x32_bf16 v[24:27], v[48:51], v[28:31], 0
	v_mfma_f32_16x16x32_bf16 v[24:27], v[52:55], v[32:35], v[24:27]
	v_mfma_f32_16x16x32_bf16 v[24:27], v[56:59], v[40:43], v[24:27]
	v_mfma_f32_16x16x32_bf16 v[24:27], v[60:63], v[44:47], v[24:27]
	ds_read_b64_tr_b16 v[56:57], v202 offset:32768
	ds_read_b64_tr_b16 v[58:59], v202 offset:34048
	s_add_u32 m0, s79, s81
	s_nop 0
	global_load_lds_dwordx4 v219, s[40:41]
	s_waitcnt lgkmcnt(13)
; __device__ __forceinline__ void phase_ssd(const Params& P, int seg, unsigned char* smem) {
;     ...
;         auto load_chunk = [&](int ci, Pre& R) { const int row0 = chunk_row0(ci);
; #pragma unroll
;             for (int i = 0; i < 2; ++i) { const int q = tid + 512 * i, l = q >> 4, c8 = q & 15; const GAS bf16* rp = xconv + (size_t)(row0 + l) * DXBC + g * 128 + c8 * 8;
;                 R.Br[i] = *(const GAS v4u*)(rp + 4096); R.Cr[i] = *(const GAS v4u*)(rp + 5120); }
;             { const int l = tid >> 3, p4 = (tid & 7) * 4; R.Xr = *(const GAS v2u*)(xconv + (size_t)(row0 + l) * DXBC + h * 64 + ph * 32 + p4);
;               R.Zr = __builtin_nontemporal_load((const GAS v2u*)(proj + (size_t)(row0 + l) * NPROJ + OFF_Z + h * 64 + ph * 32 + p4));
;               R.dtl = dtv[(size_t)(row0 + l) * 64 + h]; R.acl = acv[(size_t)(row0 + l) * 64 + h]; }
;             R.alast = acv[(size_t)(row0 + 63) * 64 + h]; R.aclane = acv[(size_t)(row0 + lane) * 64 + h]; };
;         load_chunk(0, RA); if (nchunks > 1) load_chunk(1, RB);
;         auto step = [&](int ci, Pre& R, const int par) {
;             const int row0 = chunk_row0(ci); unsigned char* sb = smem + par * T_BUF; float* acP = acS + par * 64;
;             const bf16* StR = StS + par * (T_STSZ / 2); bf16* StW = StS + (par ^ 1) * (T_STSZ / 2);
;             const float dec = __expf(R.alast);
;             { const float e2 = __expf(R.alast - R.acl);
; #pragma unroll
;               for (int i = 0; i < 2; ++i) { const int q = tid + 512 * i, l = q >> 4, c8 = q & 15; *(v4u*)(sb + T_CS + l * 272 + c8 * 16) = R.Cr[i]; *(v4u*)(sb + T_BS + l * 272 + c8 * 16) = R.Br[i]; }
;               const int l = tid >> 3, p4 = (tid & 7) * 4;
;               const float x0 = bflo(R.Xr.x) * R.dtl, x1 = bfhi(R.Xr.x) * R.dtl, x2 = bflo(R.Xr.y) * R.dtl, x3 = bfhi(R.Xr.y) * R.dtl;
;               v2u d; d.x = cvt_pk_bf16(x0, x1); d.y = cvt_pk_bf16(x2, x3); *(v2u*)(sb + T_XD + l * 80 + p4 * 2) = d;
;               v2u e; e.x = cvt_pk_bf16(x0 * e2, x1 * e2); e.y = cvt_pk_bf16(x2 * e2, x3 * e2); *(v2u*)(sb + T_XE + l * 80 + p4 * 2) = e;
;               *(v2u*)(sb + T_XS + l * 64 + p4 * 2) = R.Xr; *(v2u*)(sb + T_ZS + l * 64 + p4 * 2) = R.Zr;
;               if (w == 0) acP[lane] = R.aclane; }
;             BAR_LDS();
;             if (ci + 2 < nchunks) load_chunk(ci + 2, R);
;             bf16x8 cf[4];
; #pragma unroll
	v_mfma_f32_16x16x32_bf16 v[48:51], v[64:67], v[28:31], 0
	s_waitcnt lgkmcnt(9)
	v_mfma_f32_16x16x32_bf16 v[52:55], v[80:83], v[28:31], 0
	v_mfma_f32_16x16x32_bf16 v[48:51], v[68:71], v[32:35], v[48:51]
	s_waitcnt lgkmcnt(8)
	v_mfma_f32_16x16x32_bf16 v[52:55], v[84:87], v[32:35], v[52:55]
	v_mfma_f32_16x16x32_bf16 v[48:51], v[72:75], v[40:43], v[48:51]
	s_waitcnt lgkmcnt(7)
	v_mfma_f32_16x16x32_bf16 v[52:55], v[88:91], v[40:43], v[52:55]
	s_add_u32 m0, m0, 0x2000
	s_nop 0
	global_load_lds_dwordx4 v220, s[40:41]
	v_mfma_f32_16x16x32_bf16 v[48:51], v[76:79], v[44:47], v[48:51]
	s_waitcnt lgkmcnt(6)
	v_mfma_f32_16x16x32_bf16 v[52:55], v[92:95], v[44:47], v[52:55]
	ds_read_b128 v[64:67], v213 offset:8192
	ds_read_b128 v[68:71], v214 offset:8192
	ds_read_b128 v[72:75], v215 offset:8192
	ds_read_b128 v[76:79], v216 offset:8192
	global_load_dwordx2 v[132:133], v163, s[40:41]
	ds_read_b64_tr_b16 v[60:61], v202 offset:35328
	ds_read_b64_tr_b16 v[62:63], v202 offset:36608
	v_exp_f32_e32 v160, v151
	s_nop 0
	v_mul_f32_e32 v24, v24, v160
	v_mul_f32_e32 v25, v25, v160
	v_mul_f32_e32 v26, v26, v160
	global_load_dwordx2 v[134:135], v164, s[42:43] nt
	v_mul_f32_e32 v27, v27, v160
	s_waitcnt lgkmcnt(8)
	v_lshlrev_b32_e32 v112, 16, v126
	v_and_b32_e32 v113, 0xffff0000, v126
	v_lshlrev_b32_e32 v114, 16, v127
	v_and_b32_e32 v115, 0xffff0000, v127
	v_mul_f32_e32 v120, 0xbfb8aa3b, v112
	global_load_dword v118, v165, s[44:45]
	v_mul_f32_e32 v121, 0xbfb8aa3b, v113
	v_mul_f32_e32 v122, 0xbfb8aa3b, v114
	v_mul_f32_e32 v123, 0xbfb8aa3b, v115
	v_exp_f32_e32 v120, v120
	v_exp_f32_e32 v121, v121
	v_exp_f32_e32 v122, v122
	global_load_dword v136, v165, s[46:47]
	v_exp_f32_e32 v123, v123
	v_add_f32_e32 v120, 1.0, v120
	v_add_f32_e32 v121, 1.0, v121
	v_add_f32_e32 v122, 1.0, v122
	v_add_f32_e32 v123, 1.0, v123
	v_rcp_f32_e32 v120, v120
	global_load_dword v137, v166, s[46:47]
	v_rcp_f32_e32 v121, v121
	v_rcp_f32_e32 v122, v122
	v_rcp_f32_e32 v123, v123
	v_mul_f32_e32 v112, v120, v112
	v_mul_f32_e32 v113, v121, v113
	v_mul_f32_e32 v114, v122, v114
	s_add_u32 s66, s54, 3
	s_cmp_lt_u32 s66, s39
	s_cselect_b32 s74, 0xc0000, 0
	s_cselect_b32 s75, 0x280000, 0
	s_cselect_b32 s76, 0x4000, 0
	s_add_u32 s40, s40, s74
	s_addc_u32 s41, s41, 0
	s_add_u32 s42, s42, s75
	s_addc_u32 s43, s43, 0
	s_add_u32 s44, s44, s76
	s_addc_u32 s45, s45, 0
	s_add_u32 s46, s46, s76
	s_addc_u32 s47, s47, 0
	v_mul_f32_e32 v115, v123, v115
	v_lshlrev_b32_e32 v120, 16, v124
	s_waitcnt vmcnt(10)
	v_and_b32_e32 v121, 0xffff0000, v124
	v_lshlrev_b32_e32 v122, 16, v125
	v_sub_f32_e32 v156, v117, v116
	v_and_b32_e32 v123, 0xffff0000, v125
	v_sub_f32_e32 v140, v151, v96
	v_mul_f32_e32 v156, 0x3fb8aa3b, v156
	v_sub_f32_e32 v141, v151, v97
	v_sub_f32_e32 v142, v151, v98
	v_exp_f32_e32 v156, v156
	v_sub_f32_e32 v143, v151, v99
	v_exp_f32_e32 v140, v140
	v_lshlrev_b32_e32 v152, 16, v4
	v_exp_f32_e32 v141, v141
	v_exp_f32_e32 v142, v142
	v_and_b32_e32 v153, 0xffff0000, v4
	v_exp_f32_e32 v143, v143
	v_mul_f32_e32 v140, v48, v140
	v_lshlrev_b32_e32 v154, 16, v5
	v_mul_f32_e32 v141, v49, v141
	v_mul_f32_e32 v142, v50, v142
	v_and_b32_e32 v155, 0xffff0000, v5
	v_mul_f32_e32 v143, v51, v143
	v_sub_f32_e32 v144, v151, v100
	v_mul_f32_e32 v152, v152, v6
	v_sub_f32_e32 v145, v151, v101
	v_sub_f32_e32 v146, v151, v102
	v_mul_f32_e32 v153, v153, v6
	v_sub_f32_e32 v147, v151, v103
	v_exp_f32_e32 v144, v144
	v_mul_f32_e32 v154, v154, v6
	v_exp_f32_e32 v145, v145
	v_exp_f32_e32 v146, v146
	v_mul_f32_e32 v155, v155, v6
	v_exp_f32_e32 v147, v147
	v_mul_f32_e32 v144, v52, v144
	v_cvt_pk_bf16_f32 v158, v152, v153
	v_mul_f32_e32 v145, v53, v145
	v_mul_f32_e32 v146, v54, v146
	v_cvt_pk_bf16_f32 v159, v154, v155
	v_mul_f32_e32 v147, v55, v147
	v_cvt_pk_bf16_f32 v128, v140, v141
	ds_write_b64 v171, v[158:159] offset:32768
	v_cvt_pk_bf16_f32 v129, v142, v143
	v_cvt_pk_bf16_f32 v130, v144, v145
	v_mul_f32_e32 v152, v152, v156
	v_cvt_pk_bf16_f32 v131, v146, v147
	s_waitcnt lgkmcnt(7)
	s_nop 0
	v_mfma_f32_16x16x32_bf16 v[24:27], v[56:59], v[128:131], v[24:27]
	v_mul_f32_e32 v153, v153, v156
	ds_read_b128 v[96:99], v200 offset:384
	s_waitcnt lgkmcnt(7)
	v_mfma_f32_16x16x32_bf16 v[48:51], v[64:67], v[28:31], 0
	v_mul_f32_e32 v154, v154, v156
	s_waitcnt lgkmcnt(6)
	v_mfma_f32_16x16x32_bf16 v[48:51], v[68:71], v[32:35], v[48:51]
	s_waitcnt lgkmcnt(5)
	v_mfma_f32_16x16x32_bf16 v[48:51], v[72:75], v[40:43], v[48:51]
	v_mul_f32_e32 v155, v155, v156
	s_waitcnt lgkmcnt(4)
	v_mfma_f32_16x16x32_bf16 v[48:51], v[76:79], v[44:47], v[48:51]
	s_waitcnt lgkmcnt(0)
	v_sub_f32_e32 v140, v151, v96
	v_cvt_pk_bf16_f32 v148, v152, v153
	v_sub_f32_e32 v141, v151, v97
	v_sub_f32_e32 v142, v151, v98
	v_cvt_pk_bf16_f32 v149, v154, v155
	v_sub_f32_e32 v143, v151, v99
	v_exp_f32_e32 v140, v140
	ds_write_b64 v171, v[148:149] offset:37888
	v_exp_f32_e32 v141, v141
	v_exp_f32_e32 v142, v142
	ds_write_b64 v184, v[4:5] offset:43008
	v_exp_f32_e32 v143, v143
	v_mul_f32_e32 v140, v48, v140
	ds_write_b64 v184, v[36:37] offset:47616
	v_mul_f32_e32 v141, v49, v141
	v_mul_f32_e32 v142, v50, v142
	v_mul_f32_e32 v157, 0x3fb8aa3b, v116
	v_mul_f32_e32 v143, v51, v143
	v_cndmask_b32_e64 v140, 0, v140, s[14:15]
	ds_write_b32 v186, v157
	v_cndmask_b32_e64 v141, 0, v141, s[16:17]
	v_cndmask_b32_e64 v142, 0, v142, s[22:23]
	v_mul_f32_e32 v150, 0x3fb8aa3b, v117
	v_cndmask_b32_e64 v143, 0, v143, s[34:35]
	v_cvt_pk_bf16_f32 v128, v140, v141
	v_exp_f32_e32 v150, v150
	v_cvt_pk_bf16_f32 v129, v142, v143
	v_mov_b32_e32 v130, 0
	v_mov_b32_e32 v131, 0
	s_nop 1
	v_mfma_f32_16x16x32_bf16 v[24:27], v[60:63], v[128:131], v[24:27]
	s_mul_i32 s65, s56, 0x2000
	s_add_u32 s65, s65, 0x304f1000
	s_add_u32 s48, s0, s65
	s_addc_u32 s49, s1, 0
	s_nop 3
	v_fma_f32 v140, s61, v120, v24
	v_fma_f32 v141, s61, v121, v25
	v_fma_f32 v142, s61, v122, v26
	v_fma_f32 v143, s61, v123, v27
	v_mul_f32_e32 v140, v140, v112
	v_mul_f32_e32 v141, v141, v113
	v_mul_f32_e32 v142, v142, v114
	v_mul_f32_e32 v143, v143, v115
	v_cvt_pk_bf16_f32 v138, v140, v141
	v_cvt_pk_bf16_f32 v139, v142, v143
	global_store_dwordx2 v167, v[138:139], s[48:49]
	s_add_u32 s65, s54, 1
	s_sub_u32 s65, s65, s60
	s_lshl_b32 s65, s65, 6
	s_add_u32 s56, s65, s20
	s_waitcnt lgkmcnt(0)
	s_barrier
	s_mov_b32 s80, s77
	s_mov_b32 s77, s78
	s_mov_b32 s78, s79
	s_mov_b32 s79, s80
	s_mov_b32 s80, s82
	s_mov_b32 s82, s83
	s_mov_b32 s83, s84
	s_mov_b32 s84, s80
	s_mov_b32 s80, s85
	s_mov_b32 s85, s86
	s_mov_b32 s86, s87
	s_mov_b32 s87, s80
	s_add_u32 s54, s54, 1
	s_cmp_lt_u32 s54, s39
	s_cbranch_scc1 .Lssd_loop2
	s_branch .Lssd_done
; __device__ __forceinline__ void phase_ssd(const Params& P, int seg, unsigned char* smem) {
;     ...
;         auto load_chunk = [&](int ci, Pre& R) { const int row0 = chunk_row0(ci);
; #pragma unroll
;             for (int i = 0; i < 2; ++i) { const int q = tid + 512 * i, l = q >> 4, c8 = q & 15; const GAS bf16* rp = xconv + (size_t)(row0 + l) * DXBC + g * 128 + c8 * 8;
;                 R.Br[i] = *(const GAS v4u*)(rp + 4096); R.Cr[i] = *(const GAS v4u*)(rp + 5120); }
;             { const int l = tid >> 3, p4 = (tid & 7) * 4; R.Xr = *(const GAS v2u*)(xconv + (size_t)(row0 + l) * DXBC + h * 64 + ph * 32 + p4);
;               R.Zr = __builtin_nontemporal_load((const GAS v2u*)(proj + (size_t)(row0 + l) * NPROJ + OFF_Z + h * 64 + ph * 32 + p4));
;               R.dtl = dtv[(size_t)(row0 + l) * 64 + h]; R.acl = acv[(size_t)(row0 + l) * 64 + h]; }
;             R.alast = acv[(size_t)(row0 + 63) * 64 + h]; R.aclane = acv[(size_t)(row0 + lane) * 64 + h]; };
;         load_chunk(0, RA); if (nchunks > 1) load_chunk(1, RB);
;         auto step = [&](int ci, Pre& R, const int par) {
;             const int row0 = chunk_row0(ci); unsigned char* sb = smem + par * T_BUF; float* acP = acS + par * 64;
;             const bf16* StR = StS + par * (T_STSZ / 2); bf16* StW = StS + (par ^ 1) * (T_STSZ / 2);
;             const float dec = __expf(R.alast);
;             { const float e2 = __expf(R.alast - R.acl);
; #pragma unroll
;               for (int i = 0; i < 2; ++i) { const int q = tid + 512 * i, l = q >> 4, c8 = q & 15; *(v4u*)(sb + T_CS + l * 272 + c8 * 16) = R.Cr[i]; *(v4u*)(sb + T_BS + l * 272 + c8 * 16) = R.Br[i]; }
;               const int l = tid >> 3, p4 = (tid & 7) * 4;
;               const float x0 = bflo(R.Xr.x) * R.dtl, x1 = bfhi(R.Xr.x) * R.dtl, x2 = bflo(R.Xr.y) * R.dtl, x3 = bfhi(R.Xr.y) * R.dtl;
;               v2u d; d.x = cvt_pk_bf16(x0, x1); d.y = cvt_pk_bf16(x2, x3); *(v2u*)(sb + T_XD + l * 80 + p4 * 2) = d;
;               v2u e; e.x = cvt_pk_bf16(x0 * e2, x1 * e2); e.y = cvt_pk_bf16(x2 * e2, x3 * e2); *(v2u*)(sb + T_XE + l * 80 + p4 * 2) = e;
;               *(v2u*)(sb + T_XS + l * 64 + p4 * 2) = R.Xr; *(v2u*)(sb + T_ZS + l * 64 + p4 * 2) = R.Zr;
;               if (w == 0) acP[lane] = R.aclane; }
;             BAR_LDS();
;             if (ci + 2 < nchunks) load_chunk(ci + 2, R);
;             bf16x8 cf[4];
; #pragma unroll
.Lssd_loop3:
	v_add_u32_e32 v213, s77, v187
	v_add_u32_e32 v214, s77, v188
	v_add_u32_e32 v215, s77, v189
	v_add_u32_e32 v216, s77, v190
	v_add_u32_e32 v221, s85, v187
	v_add_u32_e32 v222, s85, v188
	v_add_u32_e32 v223, s85, v189
	v_add_u32_e32 v224, s85, v190
	ds_read_b128 v[28:31], v221 offset:4096
	ds_read_b128 v[32:35], v222 offset:4096
	ds_read_b128 v[40:43], v223 offset:4096
	ds_read_b128 v[44:47], v224 offset:4096
	ds_read_b128 v[48:51], v195
	ds_read_b128 v[52:55], v196
	ds_read_b128 v[56:59], v197
	ds_read_b128 v[60:63], v198
	ds_read_b32 v151, v199 offset:192
	ds_read_b128 v[64:67], v213
	ds_read_b128 v[68:71], v214
	ds_read_b128 v[72:75], v215
	ds_read_b128 v[76:79], v216
	ds_read_b128 v[80:83], v213 offset:4096
	ds_read_b128 v[84:87], v214 offset:4096
	s_add_u32 m0, s84, s81
	s_nop 0
	global_load_lds_dwordx4 v225, s[40:41]
	s_waitcnt lgkmcnt(11)
	ds_read_b128 v[88:91], v215 offset:4096
	ds_read_b128 v[92:95], v216 offset:4096
	ds_read_b128 v[96:99], v200
	ds_read_b128 v[100:103], v200 offset:64
	s_waitcnt lgkmcnt(11)
	ds_read_b64 v[124:125], v203 offset:46464
	ds_read_b64 v[126:127], v203 offset:51072
	v_mfma_f32_16x16x32_bf16 v[24:27], v[48:51], v[28:31], 0
	s_add_u32 m0, s87, s81
	s_nop 0
	global_load_lds_dwordx4 v226, s[40:41]
	v_mfma_f32_16x16x32_bf16 v[24:27], v[52:55], v[32:35], v[24:27]
	v_mfma_f32_16x16x32_bf16 v[24:27], v[56:59], v[40:43], v[24:27]
	v_mfma_f32_16x16x32_bf16 v[24:27], v[60:63], v[44:47], v[24:27]
	ds_read_b64_tr_b16 v[56:57], v201 offset:32768
	ds_read_b64_tr_b16 v[58:59], v201 offset:34048
	s_waitcnt lgkmcnt(13)
	v_mfma_f32_16x16x32_bf16 v[48:51], v[64:67], v[28:31], 0
	s_waitcnt lgkmcnt(9)
	v_mfma_f32_16x16x32_bf16 v[52:55], v[80:83], v[28:31], 0
	s_add_u32 m0, s79, s81
	s_nop 0
	global_load_lds_dwordx4 v219, s[40:41]
	v_mfma_f32_16x16x32_bf16 v[48:51], v[68:71], v[32:35], v[48:51]
	s_waitcnt lgkmcnt(8)
	v_mfma_f32_16x16x32_bf16 v[52:55], v[84:87], v[32:35], v[52:55]
	v_mfma_f32_16x16x32_bf16 v[48:51], v[72:75], v[40:43], v[48:51]
	s_waitcnt lgkmcnt(7)
	v_mfma_f32_16x16x32_bf16 v[52:55], v[88:91], v[40:43], v[52:55]
	v_mfma_f32_16x16x32_bf16 v[48:51], v[76:79], v[44:47], v[48:51]
	s_waitcnt lgkmcnt(6)
	v_mfma_f32_16x16x32_bf16 v[52:55], v[92:95], v[44:47], v[52:55]
	ds_read_b128 v[64:67], v213 offset:8192
	s_add_u32 m0, m0, 0x2000
	s_nop 0
	global_load_lds_dwordx4 v220, s[40:41]
	ds_read_b128 v[68:71], v214 offset:8192
	ds_read_b128 v[72:75], v215 offset:8192
	ds_read_b128 v[76:79], v216 offset:8192
	ds_read_b128 v[80:83], v213 offset:12288
	ds_read_b128 v[84:87], v214 offset:12288
	ds_read_b128 v[88:91], v215 offset:12288
	ds_read_b128 v[92:95], v216 offset:12288
	global_load_dwordx2 v[4:5], v163, s[40:41]
	ds_read_b64_tr_b16 v[60:61], v201 offset:35328
	s_waitcnt lgkmcnt(11)
	ds_read_b64_tr_b16 v[62:63], v201 offset:36608
	v_exp_f32_e32 v160, v151
	s_nop 0
	v_mul_f32_e32 v24, v24, v160
	v_mul_f32_e32 v25, v25, v160
	v_mul_f32_e32 v26, v26, v160
	v_mul_f32_e32 v27, v27, v160
	global_load_dwordx2 v[36:37], v164, s[42:43] nt
	v_lshlrev_b32_e32 v112, 16, v126
	v_and_b32_e32 v113, 0xffff0000, v126
	v_lshlrev_b32_e32 v114, 16, v127
	v_and_b32_e32 v115, 0xffff0000, v127
	v_mul_f32_e32 v120, 0xbfb8aa3b, v112
	v_mul_f32_e32 v121, 0xbfb8aa3b, v113
	v_mul_f32_e32 v122, 0xbfb8aa3b, v114
	global_load_dword v6, v165, s[44:45]
	v_mul_f32_e32 v123, 0xbfb8aa3b, v115
	v_exp_f32_e32 v120, v120
	v_exp_f32_e32 v121, v121
	v_exp_f32_e32 v122, v122
	v_exp_f32_e32 v123, v123
	v_add_f32_e32 v120, 1.0, v120
	v_add_f32_e32 v121, 1.0, v121
	global_load_dword v116, v165, s[46:47]
	v_add_f32_e32 v122, 1.0, v122
	v_add_f32_e32 v123, 1.0, v123
	v_rcp_f32_e32 v120, v120
	v_rcp_f32_e32 v121, v121
	v_rcp_f32_e32 v122, v122
	v_rcp_f32_e32 v123, v123
	v_mul_f32_e32 v112, v120, v112
	v_mul_f32_e32 v113, v121, v113
	global_load_dword v117, v166, s[46:47]
	v_mul_f32_e32 v114, v122, v114
	v_mul_f32_e32 v115, v123, v115
	v_lshlrev_b32_e32 v120, 16, v124
	v_and_b32_e32 v121, 0xffff0000, v124
	v_lshlrev_b32_e32 v122, 16, v125
	v_and_b32_e32 v123, 0xffff0000, v125
	v_sub_f32_e32 v140, v151, v96
	s_add_u32 s66, s54, 3
	s_cmp_lt_u32 s66, s39
	s_cselect_b32 s74, 0xc0000, 0
	s_cselect_b32 s75, 0x280000, 0
	s_cselect_b32 s76, 0x4000, 0
	s_add_u32 s40, s40, s74
	s_addc_u32 s41, s41, 0
	s_add_u32 s42, s42, s75
	s_addc_u32 s43, s43, 0
	s_add_u32 s44, s44, s76
	s_addc_u32 s45, s45, 0
	s_add_u32 s46, s46, s76
	s_addc_u32 s47, s47, 0
	v_sub_f32_e32 v141, v151, v97
	v_sub_f32_e32 v142, v151, v98
	s_waitcnt vmcnt(10)
	v_sub_f32_e32 v143, v151, v99
	v_exp_f32_e32 v140, v140
	v_sub_f32_e32 v156, v137, v136
	v_exp_f32_e32 v141, v141
	v_exp_f32_e32 v142, v142
	v_exp_f32_e32 v143, v143
	v_mul_f32_e32 v156, 0x3fb8aa3b, v156
	v_mul_f32_e32 v140, v48, v140
	v_mul_f32_e32 v141, v49, v141
	v_exp_f32_e32 v156, v156
	v_mul_f32_e32 v142, v50, v142
	v_mul_f32_e32 v143, v51, v143
	v_sub_f32_e32 v144, v151, v100
	v_lshlrev_b32_e32 v152, 16, v132
	v_sub_f32_e32 v145, v151, v101
	v_sub_f32_e32 v146, v151, v102
	v_and_b32_e32 v153, 0xffff0000, v132
	v_sub_f32_e32 v147, v151, v103
	v_exp_f32_e32 v144, v144
	v_lshlrev_b32_e32 v154, 16, v133
	v_exp_f32_e32 v145, v145
	v_exp_f32_e32 v146, v146
	v_exp_f32_e32 v147, v147
	v_and_b32_e32 v155, 0xffff0000, v133
	v_mul_f32_e32 v144, v52, v144
	v_mul_f32_e32 v145, v53, v145
	v_mul_f32_e32 v152, v152, v118
	v_mul_f32_e32 v146, v54, v146
	v_mul_f32_e32 v147, v55, v147
	v_mul_f32_e32 v153, v153, v118
	v_cvt_pk_bf16_f32 v128, v140, v141
	v_cvt_pk_bf16_f32 v129, v142, v143
	v_cvt_pk_bf16_f32 v130, v144, v145
	v_mul_f32_e32 v154, v154, v118
	v_cvt_pk_bf16_f32 v131, v146, v147
	s_waitcnt lgkmcnt(10)
; __device__ __forceinline__ void phase_ssd(const Params& P, int seg, unsigned char* smem) {
;     ...
;         auto load_chunk = [&](int ci, Pre& R) { const int row0 = chunk_row0(ci);
; #pragma unroll
;             for (int i = 0; i < 2; ++i) { const int q = tid + 512 * i, l = q >> 4, c8 = q & 15; const GAS bf16* rp = xconv + (size_t)(row0 + l) * DXBC + g * 128 + c8 * 8;
;                 R.Br[i] = *(const GAS v4u*)(rp + 4096); R.Cr[i] = *(const GAS v4u*)(rp + 5120); }
;             { const int l = tid >> 3, p4 = (tid & 7) * 4; R.Xr = *(const GAS v2u*)(xconv + (size_t)(row0 + l) * DXBC + h * 64 + ph * 32 + p4);
;               R.Zr = __builtin_nontemporal_load((const GAS v2u*)(proj + (size_t)(row0 + l) * NPROJ + OFF_Z + h * 64 + ph * 32 + p4));
;               R.dtl = dtv[(size_t)(row0 + l) * 64 + h]; R.acl = acv[(size_t)(row0 + l) * 64 + h]; }
;             R.alast = acv[(size_t)(row0 + 63) * 64 + h]; R.aclane = acv[(size_t)(row0 + lane) * 64 + h]; };
;         load_chunk(0, RA); if (nchunks > 1) load_chunk(1, RB);
;         auto step = [&](int ci, Pre& R, const int par) {
;             const int row0 = chunk_row0(ci); unsigned char* sb = smem + par * T_BUF; float* acP = acS + par * 64;
;             const bf16* StR = StS + par * (T_STSZ / 2); bf16* StW = StS + (par ^ 1) * (T_STSZ / 2);
;             const float dec = __expf(R.alast);
;             { const float e2 = __expf(R.alast - R.acl);
; #pragma unroll
;               for (int i = 0; i < 2; ++i) { const int q = tid + 512 * i, l = q >> 4, c8 = q & 15; *(v4u*)(sb + T_CS + l * 272 + c8 * 16) = R.Cr[i]; *(v4u*)(sb + T_BS + l * 272 + c8 * 16) = R.Br[i]; }
;               const int l = tid >> 3, p4 = (tid & 7) * 4;
;               const float x0 = bflo(R.Xr.x) * R.dtl, x1 = bfhi(R.Xr.x) * R.dtl, x2 = bflo(R.Xr.y) * R.dtl, x3 = bfhi(R.Xr.y) * R.dtl;
;               v2u d; d.x = cvt_pk_bf16(x0, x1); d.y = cvt_pk_bf16(x2, x3); *(v2u*)(sb + T_XD + l * 80 + p4 * 2) = d;
;               v2u e; e.x = cvt_pk_bf16(x0 * e2, x1 * e2); e.y = cvt_pk_bf16(x2 * e2, x3 * e2); *(v2u*)(sb + T_XE + l * 80 + p4 * 2) = e;
;               *(v2u*)(sb + T_XS + l * 64 + p4 * 2) = R.Xr; *(v2u*)(sb + T_ZS + l * 64 + p4 * 2) = R.Zr;
;               if (w == 0) acP[lane] = R.aclane; }
;             BAR_LDS();
;             if (ci + 2 < nchunks) load_chunk(ci + 2, R);
;             bf16x8 cf[4];
; #pragma unroll
	s_nop 0
	v_mfma_f32_16x16x32_bf16 v[24:27], v[56:59], v[128:131], v[24:27]
	v_mul_f32_e32 v155, v155, v118
	ds_read_b128 v[96:99], v200 offset:128
	ds_read_b128 v[100:103], v200 offset:192
	s_waitcnt lgkmcnt(11)
	v_mfma_f32_16x16x32_bf16 v[48:51], v[64:67], v[28:31], 0
	v_cvt_pk_bf16_f32 v158, v152, v153
	s_waitcnt lgkmcnt(7)
	v_mfma_f32_16x16x32_bf16 v[52:55], v[80:83], v[28:31], 0
	v_mfma_f32_16x16x32_bf16 v[48:51], v[68:71], v[32:35], v[48:51]
	v_cvt_pk_bf16_f32 v159, v154, v155
	s_waitcnt lgkmcnt(6)
	v_mfma_f32_16x16x32_bf16 v[52:55], v[84:87], v[32:35], v[52:55]
	v_mfma_f32_16x16x32_bf16 v[48:51], v[72:75], v[40:43], v[48:51]
	ds_write_b64 v174, v[158:159] offset:32768
	s_waitcnt lgkmcnt(6)
	v_mfma_f32_16x16x32_bf16 v[52:55], v[88:91], v[40:43], v[52:55]
	v_mfma_f32_16x16x32_bf16 v[48:51], v[76:79], v[44:47], v[48:51]
	s_waitcnt lgkmcnt(5)
	v_mfma_f32_16x16x32_bf16 v[52:55], v[92:95], v[44:47], v[52:55]
	v_mul_f32_e32 v152, v152, v156
	s_waitcnt lgkmcnt(2)
	v_sub_f32_e32 v140, v151, v96
	v_sub_f32_e32 v141, v151, v97
	v_mul_f32_e32 v153, v153, v156
	v_sub_f32_e32 v142, v151, v98
	v_sub_f32_e32 v143, v151, v99
	v_mul_f32_e32 v154, v154, v156
	v_exp_f32_e32 v140, v140
	v_exp_f32_e32 v141, v141
	v_exp_f32_e32 v142, v142
	v_mul_f32_e32 v155, v155, v156
	v_exp_f32_e32 v143, v143
	v_mul_f32_e32 v140, v48, v140
	v_cvt_pk_bf16_f32 v148, v152, v153
	v_mul_f32_e32 v141, v49, v141
	v_mul_f32_e32 v142, v50, v142
	v_mul_f32_e32 v143, v51, v143
	v_cvt_pk_bf16_f32 v149, v154, v155
	s_waitcnt lgkmcnt(1)
	v_sub_f32_e32 v144, v151, v100
	v_sub_f32_e32 v145, v151, v101
	ds_write_b64 v174, v[148:149] offset:37888
	v_sub_f32_e32 v146, v151, v102
	v_sub_f32_e32 v147, v151, v103
	ds_write_b64 v185, v[132:133] offset:43008
	v_exp_f32_e32 v144, v144
	v_exp_f32_e32 v145, v145
	v_exp_f32_e32 v146, v146
	ds_write_b64 v185, v[134:135] offset:47616
	v_exp_f32_e32 v147, v147
	v_mul_f32_e32 v144, v52, v144
	v_mul_f32_e32 v157, 0x3fb8aa3b, v136
	v_mul_f32_e32 v145, v53, v145
	v_mul_f32_e32 v146, v54, v146
	ds_write_b32 v186, v157 offset:256
	v_mul_f32_e32 v147, v55, v147
	v_cndmask_b32_e64 v144, 0, v144, s[14:15]
	v_cndmask_b32_e64 v145, 0, v145, s[16:17]
	v_mul_f32_e32 v150, 0x3fb8aa3b, v137
	v_cndmask_b32_e64 v146, 0, v146, s[22:23]
	v_cndmask_b32_e64 v147, 0, v147, s[34:35]
	v_exp_f32_e32 v150, v150
	v_cvt_pk_bf16_f32 v128, v140, v141
	v_cvt_pk_bf16_f32 v129, v142, v143
	v_cvt_pk_bf16_f32 v130, v144, v145
	v_cvt_pk_bf16_f32 v131, v146, v147
	s_nop 1
	v_mfma_f32_16x16x32_bf16 v[24:27], v[60:63], v[128:131], v[24:27]
	s_mul_i32 s65, s56, 0x2000
	s_add_u32 s65, s65, 0x304f1000
	s_add_u32 s48, s0, s65
	s_addc_u32 s49, s1, 0
	s_nop 3
	v_fma_f32 v140, s61, v120, v24
	v_fma_f32 v141, s61, v121, v25
	v_fma_f32 v142, s61, v122, v26
	v_fma_f32 v143, s61, v123, v27
	v_mul_f32_e32 v140, v140, v112
	v_mul_f32_e32 v141, v141, v113
	v_mul_f32_e32 v142, v142, v114
	v_mul_f32_e32 v143, v143, v115
	v_cvt_pk_bf16_f32 v138, v140, v141
	v_cvt_pk_bf16_f32 v139, v142, v143
	global_store_dwordx2 v167, v[138:139], s[48:49]
	s_add_u32 s65, s54, 1
	s_sub_u32 s65, s65, s60
	s_lshl_b32 s65, s65, 6
	s_add_u32 s56, s65, s20
	s_waitcnt lgkmcnt(0)
	s_barrier
	s_mov_b32 s80, s77
	s_mov_b32 s77, s78
	s_mov_b32 s78, s79
	s_mov_b32 s79, s80
	s_mov_b32 s80, s82
	s_mov_b32 s82, s83
	s_mov_b32 s83, s84
	s_mov_b32 s84, s80
	s_mov_b32 s80, s85
	s_mov_b32 s85, s86
	s_mov_b32 s86, s87
	s_mov_b32 s87, s80
	s_add_u32 s54, s54, 1
	s_cmp_ge_u32 s54, s39
	s_cbranch_scc1 .Lssd_done
	v_add_u32_e32 v213, s77, v187
	v_add_u32_e32 v214, s77, v188
	v_add_u32_e32 v215, s77, v189
	v_add_u32_e32 v216, s77, v190
	v_add_u32_e32 v221, s85, v187
	v_add_u32_e32 v222, s85, v188
	v_add_u32_e32 v223, s85, v189
	v_add_u32_e32 v224, s85, v190
	ds_read_b128 v[28:31], v221 offset:4096
	ds_read_b128 v[32:35], v222 offset:4096
	ds_read_b128 v[40:43], v223 offset:4096
	ds_read_b128 v[44:47], v224 offset:4096
	ds_read_b128 v[48:51], v195 offset:8192
	ds_read_b128 v[52:55], v196 offset:8192
	ds_read_b128 v[56:59], v197 offset:8192
	ds_read_b128 v[60:63], v198 offset:8192
	ds_read_b32 v151, v199 offset:448
	ds_read_b128 v[64:67], v213
	ds_read_b128 v[68:71], v214
	ds_read_b128 v[72:75], v215
	ds_read_b128 v[76:79], v216
	ds_read_b128 v[80:83], v213 offset:4096
	ds_read_b128 v[84:87], v214 offset:4096
	s_add_u32 m0, s84, s81
	s_nop 0
	global_load_lds_dwordx4 v225, s[40:41]
	s_waitcnt lgkmcnt(11)
	ds_read_b128 v[88:91], v215 offset:4096
	ds_read_b128 v[92:95], v216 offset:4096
	ds_read_b128 v[96:99], v200 offset:256
	ds_read_b128 v[100:103], v200 offset:320
	s_waitcnt lgkmcnt(11)
	ds_read_b64 v[124:125], v204 offset:46464
	ds_read_b64 v[126:127], v204 offset:51072
	v_mfma_f32_16x16x32_bf16 v[24:27], v[48:51], v[28:31], 0
	s_add_u32 m0, s87, s81
	s_nop 0
	global_load_lds_dwordx4 v226, s[40:41]
	v_mfma_f32_16x16x32_bf16 v[24:27], v[52:55], v[32:35], v[24:27]
	v_mfma_f32_16x16x32_bf16 v[24:27], v[56:59], v[40:43], v[24:27]
	v_mfma_f32_16x16x32_bf16 v[24:27], v[60:63], v[44:47], v[24:27]
	ds_read_b64_tr_b16 v[56:57], v202 offset:32768
	ds_read_b64_tr_b16 v[58:59], v202 offset:34048
	s_waitcnt lgkmcnt(13)
	v_mfma_f32_16x16x32_bf16 v[48:51], v[64:67], v[28:31], 0
	s_waitcnt lgkmcnt(9)
	v_mfma_f32_16x16x32_bf16 v[52:55], v[80:83], v[28:31], 0
	s_add_u32 m0, s79, s81
	s_nop 0
	global_load_lds_dwordx4 v219, s[40:41]
	v_mfma_f32_16x16x32_bf16 v[48:51], v[68:71], v[32:35], v[48:51]
	s_waitcnt lgkmcnt(8)
	v_mfma_f32_16x16x32_bf16 v[52:55], v[84:87], v[32:35], v[52:55]
	v_mfma_f32_16x16x32_bf16 v[48:51], v[72:75], v[40:43], v[48:51]
	s_waitcnt lgkmcnt(7)
	v_mfma_f32_16x16x32_bf16 v[52:55], v[88:91], v[40:43], v[52:55]
	v_mfma_f32_16x16x32_bf16 v[48:51], v[76:79], v[44:47], v[48:51]
	s_waitcnt lgkmcnt(6)
; __device__ __forceinline__ void phase_ssd(const Params& P, int seg, unsigned char* smem) {
;     ...
;         auto load_chunk = [&](int ci, Pre& R) { const int row0 = chunk_row0(ci);
; #pragma unroll
;             for (int i = 0; i < 2; ++i) { const int q = tid + 512 * i, l = q >> 4, c8 = q & 15; const GAS bf16* rp = xconv + (size_t)(row0 + l) * DXBC + g * 128 + c8 * 8;
;                 R.Br[i] = *(const GAS v4u*)(rp + 4096); R.Cr[i] = *(const GAS v4u*)(rp + 5120); }
;             { const int l = tid >> 3, p4 = (tid & 7) * 4; R.Xr = *(const GAS v2u*)(xconv + (size_t)(row0 + l) * DXBC + h * 64 + ph * 32 + p4);
;               R.Zr = __builtin_nontemporal_load((const GAS v2u*)(proj + (size_t)(row0 + l) * NPROJ + OFF_Z + h * 64 + ph * 32 + p4));
;               R.dtl = dtv[(size_t)(row0 + l) * 64 + h]; R.acl = acv[(size_t)(row0 + l) * 64 + h]; }
;             R.alast = acv[(size_t)(row0 + 63) * 64 + h]; R.aclane = acv[(size_t)(row0 + lane) * 64 + h]; };
;         load_chunk(0, RA); if (nchunks > 1) load_chunk(1, RB);
;         auto step = [&](int ci, Pre& R, const int par) {
;             const int row0 = chunk_row0(ci); unsigned char* sb = smem + par * T_BUF; float* acP = acS + par * 64;
;             const bf16* StR = StS + par * (T_STSZ / 2); bf16* StW = StS + (par ^ 1) * (T_STSZ / 2);
;             const float dec = __expf(R.alast);
;             { const float e2 = __expf(R.alast - R.acl);
; #pragma unroll
;               for (int i = 0; i < 2; ++i) { const int q = tid + 512 * i, l = q >> 4, c8 = q & 15; *(v4u*)(sb + T_CS + l * 272 + c8 * 16) = R.Cr[i]; *(v4u*)(sb + T_BS + l * 272 + c8 * 16) = R.Br[i]; }
;               const int l = tid >> 3, p4 = (tid & 7) * 4;
;               const float x0 = bflo(R.Xr.x) * R.dtl, x1 = bfhi(R.Xr.x) * R.dtl, x2 = bflo(R.Xr.y) * R.dtl, x3 = bfhi(R.Xr.y) * R.dtl;
;               v2u d; d.x = cvt_pk_bf16(x0, x1); d.y = cvt_pk_bf16(x2, x3); *(v2u*)(sb + T_XD + l * 80 + p4 * 2) = d;
;               v2u e; e.x = cvt_pk_bf16(x0 * e2, x1 * e2); e.y = cvt_pk_bf16(x2 * e2, x3 * e2); *(v2u*)(sb + T_XE + l * 80 + p4 * 2) = e;
;               *(v2u*)(sb + T_XS + l * 64 + p4 * 2) = R.Xr; *(v2u*)(sb + T_ZS + l * 64 + p4 * 2) = R.Zr;
;               if (w == 0) acP[lane] = R.aclane; }
;             BAR_LDS();
;             if (ci + 2 < nchunks) load_chunk(ci + 2, R);
;             bf16x8 cf[4];
; #pragma unroll
	v_mfma_f32_16x16x32_bf16 v[52:55], v[92:95], v[44:47], v[52:55]
	ds_read_b128 v[64:67], v213 offset:8192
	s_add_u32 m0, m0, 0x2000
	s_nop 0
	global_load_lds_dwordx4 v220, s[40:41]
	ds_read_b128 v[68:71], v214 offset:8192
	ds_read_b128 v[72:75], v215 offset:8192
	ds_read_b128 v[76:79], v216 offset:8192
	ds_read_b128 v[80:83], v213 offset:12288
	ds_read_b128 v[84:87], v214 offset:12288
	ds_read_b128 v[88:91], v215 offset:12288
	ds_read_b128 v[92:95], v216 offset:12288
	global_load_dwordx2 v[132:133], v163, s[40:41]
	ds_read_b64_tr_b16 v[60:61], v202 offset:35328
	s_waitcnt lgkmcnt(11)
	ds_read_b64_tr_b16 v[62:63], v202 offset:36608
	v_exp_f32_e32 v160, v151
	s_nop 0
	v_mul_f32_e32 v24, v24, v160
	v_mul_f32_e32 v25, v25, v160
	v_mul_f32_e32 v26, v26, v160
	v_mul_f32_e32 v27, v27, v160
	global_load_dwordx2 v[134:135], v164, s[42:43] nt
	v_lshlrev_b32_e32 v112, 16, v126
	v_and_b32_e32 v113, 0xffff0000, v126
	v_lshlrev_b32_e32 v114, 16, v127
	v_and_b32_e32 v115, 0xffff0000, v127
	v_mul_f32_e32 v120, 0xbfb8aa3b, v112
	v_mul_f32_e32 v121, 0xbfb8aa3b, v113
	v_mul_f32_e32 v122, 0xbfb8aa3b, v114
	global_load_dword v118, v165, s[44:45]
	v_mul_f32_e32 v123, 0xbfb8aa3b, v115
	v_exp_f32_e32 v120, v120
	v_exp_f32_e32 v121, v121
	v_exp_f32_e32 v122, v122
	v_exp_f32_e32 v123, v123
	v_add_f32_e32 v120, 1.0, v120
	v_add_f32_e32 v121, 1.0, v121
	global_load_dword v136, v165, s[46:47]
	v_add_f32_e32 v122, 1.0, v122
	v_add_f32_e32 v123, 1.0, v123
	v_rcp_f32_e32 v120, v120
	v_rcp_f32_e32 v121, v121
	v_rcp_f32_e32 v122, v122
	v_rcp_f32_e32 v123, v123
	v_mul_f32_e32 v112, v120, v112
	v_mul_f32_e32 v113, v121, v113
	global_load_dword v137, v166, s[46:47]
	v_mul_f32_e32 v114, v122, v114
	v_mul_f32_e32 v115, v123, v115
	v_lshlrev_b32_e32 v120, 16, v124
	v_and_b32_e32 v121, 0xffff0000, v124
	v_lshlrev_b32_e32 v122, 16, v125
	v_and_b32_e32 v123, 0xffff0000, v125
	v_sub_f32_e32 v140, v151, v96
	s_add_u32 s66, s54, 3
	s_cmp_lt_u32 s66, s39
	s_cselect_b32 s74, 0xc0000, 0
	s_cselect_b32 s75, 0x280000, 0
	s_cselect_b32 s76, 0x4000, 0
	s_add_u32 s40, s40, s74
	s_addc_u32 s41, s41, 0
	s_add_u32 s42, s42, s75
	s_addc_u32 s43, s43, 0
	s_add_u32 s44, s44, s76
	s_addc_u32 s45, s45, 0
	s_add_u32 s46, s46, s76
	s_addc_u32 s47, s47, 0
	v_sub_f32_e32 v141, v151, v97
	v_sub_f32_e32 v142, v151, v98
	s_waitcnt vmcnt(10)
	v_sub_f32_e32 v143, v151, v99
	v_exp_f32_e32 v140, v140
	v_sub_f32_e32 v156, v117, v116
	v_exp_f32_e32 v141, v141
	v_exp_f32_e32 v142, v142
	v_exp_f32_e32 v143, v143
	v_mul_f32_e32 v156, 0x3fb8aa3b, v156
	v_mul_f32_e32 v140, v48, v140
	v_mul_f32_e32 v141, v49, v141
	v_exp_f32_e32 v156, v156
	v_mul_f32_e32 v142, v50, v142
	v_mul_f32_e32 v143, v51, v143
	v_sub_f32_e32 v144, v151, v100
	v_lshlrev_b32_e32 v152, 16, v4
	v_sub_f32_e32 v145, v151, v101
	v_sub_f32_e32 v146, v151, v102
	v_and_b32_e32 v153, 0xffff0000, v4
	v_sub_f32_e32 v147, v151, v103
	v_exp_f32_e32 v144, v144
	v_lshlrev_b32_e32 v154, 16, v5
	v_exp_f32_e32 v145, v145
	v_exp_f32_e32 v146, v146
	v_exp_f32_e32 v147, v147
	v_and_b32_e32 v155, 0xffff0000, v5
	v_mul_f32_e32 v144, v52, v144
	v_mul_f32_e32 v145, v53, v145
	v_mul_f32_e32 v152, v152, v6
	v_mul_f32_e32 v146, v54, v146
	v_mul_f32_e32 v147, v55, v147
	v_mul_f32_e32 v153, v153, v6
	v_cvt_pk_bf16_f32 v128, v140, v141
	v_cvt_pk_bf16_f32 v129, v142, v143
	v_cvt_pk_bf16_f32 v130, v144, v145
	v_mul_f32_e32 v154, v154, v6
	v_cvt_pk_bf16_f32 v131, v146, v147
	s_waitcnt lgkmcnt(10)
	s_nop 0
	v_mfma_f32_16x16x32_bf16 v[24:27], v[56:59], v[128:131], v[24:27]
	v_mul_f32_e32 v155, v155, v6
	ds_read_b128 v[96:99], v200 offset:384
	ds_read_b128 v[100:103], v200 offset:448
	s_waitcnt lgkmcnt(11)
	v_mfma_f32_16x16x32_bf16 v[48:51], v[64:67], v[28:31], 0
	v_cvt_pk_bf16_f32 v158, v152, v153
	s_waitcnt lgkmcnt(7)
	v_mfma_f32_16x16x32_bf16 v[52:55], v[80:83], v[28:31], 0
	v_mfma_f32_16x16x32_bf16 v[48:51], v[68:71], v[32:35], v[48:51]
	v_cvt_pk_bf16_f32 v159, v154, v155
	s_waitcnt lgkmcnt(6)
	v_mfma_f32_16x16x32_bf16 v[52:55], v[84:87], v[32:35], v[52:55]
	v_mfma_f32_16x16x32_bf16 v[48:51], v[72:75], v[40:43], v[48:51]
	ds_write_b64 v171, v[158:159] offset:32768
	s_waitcnt lgkmcnt(6)
	v_mfma_f32_16x16x32_bf16 v[52:55], v[88:91], v[40:43], v[52:55]
	v_mfma_f32_16x16x32_bf16 v[48:51], v[76:79], v[44:47], v[48:51]
	s_waitcnt lgkmcnt(5)
	v_mfma_f32_16x16x32_bf16 v[52:55], v[92:95], v[44:47], v[52:55]
	v_mul_f32_e32 v152, v152, v156
	s_waitcnt lgkmcnt(2)
	v_sub_f32_e32 v140, v151, v96
	v_sub_f32_e32 v141, v151, v97
	v_mul_f32_e32 v153, v153, v156
	v_sub_f32_e32 v142, v151, v98
	v_sub_f32_e32 v143, v151, v99
	v_mul_f32_e32 v154, v154, v156
	v_exp_f32_e32 v140, v140
	v_exp_f32_e32 v141, v141
	v_exp_f32_e32 v142, v142
	v_mul_f32_e32 v155, v155, v156
	v_exp_f32_e32 v143, v143
	v_mul_f32_e32 v140, v48, v140
	v_cvt_pk_bf16_f32 v148, v152, v153
	v_mul_f32_e32 v141, v49, v141
	v_mul_f32_e32 v142, v50, v142
	v_mul_f32_e32 v143, v51, v143
	v_cvt_pk_bf16_f32 v149, v154, v155
	s_waitcnt lgkmcnt(1)
	v_sub_f32_e32 v144, v151, v100
	v_sub_f32_e32 v145, v151, v101
	ds_write_b64 v171, v[148:149] offset:37888
	v_sub_f32_e32 v146, v151, v102
	v_sub_f32_e32 v147, v151, v103
	ds_write_b64 v184, v[4:5] offset:43008
	v_exp_f32_e32 v144, v144
	v_exp_f32_e32 v145, v145
	v_exp_f32_e32 v146, v146
	ds_write_b64 v184, v[36:37] offset:47616
	v_exp_f32_e32 v147, v147
	v_mul_f32_e32 v144, v52, v144
	v_mul_f32_e32 v157, 0x3fb8aa3b, v116
	v_mul_f32_e32 v145, v53, v145
	v_mul_f32_e32 v146, v54, v146
	ds_write_b32 v186, v157
	v_mul_f32_e32 v147, v55, v147
	v_cndmask_b32_e64 v144, 0, v144, s[14:15]
	v_cndmask_b32_e64 v145, 0, v145, s[16:17]
	v_mul_f32_e32 v150, 0x3fb8aa3b, v117
	v_cndmask_b32_e64 v146, 0, v146, s[22:23]
	v_cndmask_b32_e64 v147, 0, v147, s[34:35]
	v_exp_f32_e32 v150, v150
	v_cvt_pk_bf16_f32 v128, v140, v141
	v_cvt_pk_bf16_f32 v129, v142, v143
	v_cvt_pk_bf16_f32 v130, v144, v145
	v_cvt_pk_bf16_f32 v131, v146, v147
	s_nop 1
	v_mfma_f32_16x16x32_bf16 v[24:27], v[60:63], v[128:131], v[24:27]
	s_mul_i32 s65, s56, 0x2000
	s_add_u32 s65, s65, 0x304f1000
	s_add_u32 s48, s0, s65
	s_addc_u32 s49, s1, 0
	s_nop 3
	v_fma_f32 v140, s61, v120, v24
	v_fma_f32 v141, s61, v121, v25
	v_fma_f32 v142, s61, v122, v26
	v_fma_f32 v143, s61, v123, v27
	v_mul_f32_e32 v140, v140, v112
	v_mul_f32_e32 v141, v141, v113
	v_mul_f32_e32 v142, v142, v114
	v_mul_f32_e32 v143, v143, v115
	v_cvt_pk_bf16_f32 v138, v140, v141
	v_cvt_pk_bf16_f32 v139, v142, v143
	global_store_dwordx2 v167, v[138:139], s[48:49]
	s_add_u32 s65, s54, 1
	s_sub_u32 s65, s65, s60
	s_lshl_b32 s65, s65, 6
	s_add_u32 s56, s65, s20
	s_waitcnt lgkmcnt(0)
	s_barrier
	s_mov_b32 s80, s77
	s_mov_b32 s77, s78
	s_mov_b32 s78, s79
	s_mov_b32 s79, s80
	s_mov_b32 s80, s82
	s_mov_b32 s82, s83
	s_mov_b32 s83, s84
	s_mov_b32 s84, s80
	s_mov_b32 s80, s85
	s_mov_b32 s85, s86
	s_mov_b32 s86, s87
	s_mov_b32 s87, s80
	s_add_u32 s54, s54, 1
	s_cmp_lt_u32 s54, s39
	s_cbranch_scc1 .Lssd_loop3
; __device__ __forceinline__ void phase_ssd(const Params& P, int seg, unsigned char* smem) {
;     ...
;         if (seg + 1 < NSEG) {
; #pragma unroll
;             for (int p2 = 0; p2 < 2; ++p2)
; #pragma unroll
;                 for (int j = 0; j < 4; ++j) stw[(size_t)(p2 * 16 + fq * 4 + j) * 128 + w * 16 + fr] = st[p2][j]; }
.Lssd_done:
	s_cmp_eq_u32 s24, 3
	s_cbranch_scc1 .Lssd_nostore
	s_cmp_ge_u32 s55, 2
	s_cbranch_scc1 .Lssd_nostore
	s_nop 7
	v_add_u32_e32 v141, 0x2000, v168
	global_store_dwordx4 v168, v[8:11], s[50:51]
	global_store_dwordx4 v141, v[12:15], s[50:51]
	global_store_dwordx4 v168, v[16:19], s[50:51] offset:64
	global_store_dwordx4 v141, v[20:23], s[50:51] offset:64
